# K-loops: s_setprio 1 raised before the opening barrier of each MFMA segment (redundant lgkmcnt wait dropped), s_setprio 0 moved after the closing barrier
# speedup vs baseline: 1.0062x; 1.0053x over previous
; #define PG8_STAGE(bufoff, gbase, voff) do { _Pragma("unroll") for (int _i = 0; _i < 2; ++_i) \
;         __builtin_amdgcn_global_load_lds((const unsigned*)((const char*)(gbase) + (voff)[_i]), (PG8_LAS unsigned*)(lds + (bufoff) + ldsw + _i * 8192), 16, 0, 0); } while (0)
; #define PG8_LDA(dst, b, h) do { _Pragma("unroll") for (int m = 0; m < 4; ++m) _Pragma("unroll") for (int k = 0; k < 2; ++k) dst[m][k] = *(const PG8_LAS bf16x8*)(lds + PG8_SA(b, h) + aoff + m * 2048 + k * 1024); } while (0)
; #define PG8_LDB(dst, b, h) do { _Pragma("unroll") for (int n = 0; n < 2; ++n) _Pragma("unroll") for (int k = 0; k < 2; ++k) dst[n][k] = *(const PG8_LAS bf16x8*)(lds + PG8_SB(b, h) + boff + n * 2048 + k * 1024); } while (0)
; #define PG8_MMA(ai, bj, At, Bt) do { __builtin_amdgcn_s_setprio(1); _Pragma("unroll") for (int m = 0; m < 4; ++m) _Pragma("unroll") for (int n = 0; n < 2; ++n) _Pragma("unroll") for (int k = 0; k < 2; ++k) \
;         acc[ai][bj][m][n] = __builtin_amdgcn_mfma_f32_16x16x32_bf16(Bt[n][k], At[m][k], acc[ai][bj][m][n], 0, 0, 0); __builtin_amdgcn_s_setprio(0); } while (0)
; #define PG8_WAIT_V(n) asm volatile("s_waitcnt vmcnt(" #n ")" ::: "memory")
; #define PG8_WAIT_L(n) asm volatile("s_waitcnt lgkmcnt(" #n ")" ::: "memory")
; #define PG8_BAR __builtin_amdgcn_s_barrier()
; #define PG8_SCHED __builtin_amdgcn_sched_barrier(0)
; template <class Epi, class Sched, bool ALIGN_EPI = false, bool SP2 = false>
; __device__ __forceinline__ void gemm_phase(PG8_LAS unsigned char* lds, const Gemm g, const Sched& S, const Epi& E) {
;     ...
;             PG8_LDB(B0, 0, 0); PG8_LDB(B1, 0, 1); PG8_SCHED; PG8_LDA(At, 0, 0); PG8_STAGE(PG8_SA(1, 1), a1 + hstep, voffA);
;             PG8_WAIT_V(8); PG8_WAIT_L(0); PG8_BAR; PG8_MMA(0, 0, At, B0); PG8_MMA(0, 1, At, B1); PG8_BAR; PG8_SCHED;
;             PG8_LDA(At, 0, 1); PG8_STAGE(PG8_SB(0, 0), b2, voffB); PG8_STAGE(PG8_SB(0, 1), b2 + hstep, voffB); PG8_STAGE(PG8_SA(0, 0), a2, voffA);
;             PG8_WAIT_V(8); PG8_WAIT_L(0); PG8_BAR; PG8_MMA(1, 0, At, B0); PG8_MMA(1, 1, At, B1); PG8_BAR; PG8_SCHED;
.LBB0_139:
	ds_read_b128 v[144:147], v160
	ds_read_b128 v[164:167], v160 offset:1024
	ds_read_b128 v[172:175], v160 offset:2048
	ds_read_b128 v[176:179], v160 offset:3072
	ds_read_b128 v[180:183], v161
	ds_read_b128 v[184:187], v161 offset:1024
	ds_read_b128 v[188:191], v161 offset:2048
	ds_read_b128 v[192:195], v161 offset:3072
	s_add_u32 s34, s30, 0xfff80080
	s_addc_u32 s35, s31, -1
	s_cmp_eq_u32 s84, 28
	s_cselect_b32 s49, s23, s35
	s_cselect_b32 s48, s80, s34
	s_cselect_b32 s35, s21, s83
	s_cselect_b32 s34, s81, s82
	v_lshl_add_u64 v[168:169], s[30:31], 0, v[136:137]
	s_add_i32 m0, s29, 0xc000
	ds_read_b128 v[196:199], v162
	ds_read_b128 v[200:203], v162 offset:1024
	ds_read_b128 v[204:207], v162 offset:2048
	ds_read_b128 v[208:211], v162 offset:3072
	ds_read_b128 v[212:215], v162 offset:4096
	ds_read_b128 v[216:219], v162 offset:5120
	ds_read_b128 v[220:223], v162 offset:6144
	ds_read_b128 v[224:227], v162 offset:7168
	global_load_lds_dwordx4 v[168:169], off
	v_lshl_add_u64 v[168:169], s[30:31], 0, v[138:139]
	s_add_i32 m0, s29, 0xe000
	s_nop 0
	global_load_lds_dwordx4 v[168:169], off
	s_waitcnt vmcnt(8)
	s_waitcnt lgkmcnt(0)
	s_setprio 1
	s_barrier
	v_mfma_f32_16x16x32_bf16 v[124:127], v[144:147], v[196:199], v[124:127]
	v_mfma_f32_16x16x32_bf16 v[120:123], v[172:175], v[196:199], v[120:123]
	v_mfma_f32_16x16x32_bf16 v[116:119], v[144:147], v[204:207], v[116:119]
	v_mfma_f32_16x16x32_bf16 v[108:111], v[172:175], v[204:207], v[108:111]
	v_mfma_f32_16x16x32_bf16 v[100:103], v[144:147], v[212:215], v[100:103]
	v_mfma_f32_16x16x32_bf16 v[92:95], v[172:175], v[212:215], v[92:95]
	v_mfma_f32_16x16x32_bf16 v[84:87], v[144:147], v[220:223], v[84:87]
	v_mfma_f32_16x16x32_bf16 v[76:79], v[172:175], v[220:223], v[76:79]
	v_mfma_f32_16x16x32_bf16 v[124:127], v[164:167], v[200:203], v[124:127]
	v_mfma_f32_16x16x32_bf16 v[120:123], v[176:179], v[200:203], v[120:123]
	v_mfma_f32_16x16x32_bf16 v[116:119], v[164:167], v[208:211], v[116:119]
	v_mfma_f32_16x16x32_bf16 v[108:111], v[176:179], v[208:211], v[108:111]
	v_mfma_f32_16x16x32_bf16 v[100:103], v[164:167], v[216:219], v[100:103]
	v_mfma_f32_16x16x32_bf16 v[92:95], v[176:179], v[216:219], v[92:95]
	v_mfma_f32_16x16x32_bf16 v[84:87], v[164:167], v[224:227], v[84:87]
	v_mfma_f32_16x16x32_bf16 v[76:79], v[176:179], v[224:227], v[76:79]
	s_setprio 0
	s_setprio 1
	v_mfma_f32_16x16x32_bf16 v[112:115], v[180:183], v[196:199], v[112:115]
	v_mfma_f32_16x16x32_bf16 v[104:107], v[188:191], v[196:199], v[104:107]
	v_mfma_f32_16x16x32_bf16 v[96:99], v[180:183], v[204:207], v[96:99]
	v_mfma_f32_16x16x32_bf16 v[88:91], v[188:191], v[204:207], v[88:91]
	v_mfma_f32_16x16x32_bf16 v[80:83], v[180:183], v[212:215], v[80:83]
	v_mfma_f32_16x16x32_bf16 v[72:75], v[188:191], v[212:215], v[72:75]
	v_mfma_f32_16x16x32_bf16 v[68:71], v[180:183], v[220:223], v[68:71]
	v_mfma_f32_16x16x32_bf16 v[64:67], v[188:191], v[220:223], v[64:67]
	v_mfma_f32_16x16x32_bf16 v[112:115], v[184:187], v[200:203], v[112:115]
	v_mfma_f32_16x16x32_bf16 v[104:107], v[192:195], v[200:203], v[104:107]
	v_mfma_f32_16x16x32_bf16 v[96:99], v[184:187], v[208:211], v[96:99]
	v_mfma_f32_16x16x32_bf16 v[88:91], v[192:195], v[208:211], v[88:91]
	v_mfma_f32_16x16x32_bf16 v[80:83], v[184:187], v[216:219], v[80:83]
	v_mfma_f32_16x16x32_bf16 v[72:75], v[192:195], v[216:219], v[72:75]
	v_mfma_f32_16x16x32_bf16 v[68:71], v[184:187], v[224:227], v[68:71]
	v_mfma_f32_16x16x32_bf16 v[64:67], v[192:195], v[224:227], v[64:67]
	s_barrier
	s_setprio 0
	s_add_i32 s36, s76, s3
	v_lshl_add_u64 v[168:169], s[34:35], 0, v[132:133]
	s_mov_b32 m0, s36
	ds_read_b128 v[196:199], v162 offset:16384
	ds_read_b128 v[200:203], v162 offset:17408
	ds_read_b128 v[204:207], v162 offset:18432
	ds_read_b128 v[208:211], v162 offset:19456
	ds_read_b128 v[212:215], v162 offset:20480
	ds_read_b128 v[216:219], v162 offset:21504
	ds_read_b128 v[220:223], v162 offset:22528
	ds_read_b128 v[224:227], v162 offset:23552
	global_load_lds_dwordx4 v[168:169], off
	s_add_i32 m0, s36, 0x2000
	s_add_u32 s36, s34, 0x80000
	v_lshl_add_u64 v[228:229], s[34:35], 0, v[128:129]
	s_addc_u32 s37, s35, 0
	s_add_i32 s58, s77, s3
	global_load_lds_dwordx4 v[228:229], off
	v_lshl_add_u64 v[230:231], s[36:37], 0, v[132:133]
	s_mov_b32 m0, s58
	v_lshl_add_u64 v[232:233], s[48:49], 0, v[130:131]
	global_load_lds_dwordx4 v[230:231], off
	v_lshl_add_u64 v[230:231], s[36:37], 0, v[128:129]
	s_add_i32 m0, s58, 0x2000
	s_nop 0
	global_load_lds_dwordx4 v[230:231], off
	v_lshl_add_u64 v[230:231], s[48:49], 0, v[134:135]
	s_mov_b32 m0, s29
	s_nop 0
	global_load_lds_dwordx4 v[230:231], off
	s_mov_b32 m0, s53
	s_nop 0
	global_load_lds_dwordx4 v[232:233], off
	s_waitcnt vmcnt(8)
	s_waitcnt lgkmcnt(0)
	s_setprio 1
	s_barrier
; #define PG8_STAGE(bufoff, gbase, voff) do { _Pragma("unroll") for (int _i = 0; _i < 2; ++_i) \
;         __builtin_amdgcn_global_load_lds((const unsigned*)((const char*)(gbase) + (voff)[_i]), (PG8_LAS unsigned*)(lds + (bufoff) + ldsw + _i * 8192), 16, 0, 0); } while (0)
; #define PG8_LDA(dst, b, h) do { _Pragma("unroll") for (int m = 0; m < 4; ++m) _Pragma("unroll") for (int k = 0; k < 2; ++k) dst[m][k] = *(const PG8_LAS bf16x8*)(lds + PG8_SA(b, h) + aoff + m * 2048 + k * 1024); } while (0)
; #define PG8_LDB(dst, b, h) do { _Pragma("unroll") for (int n = 0; n < 2; ++n) _Pragma("unroll") for (int k = 0; k < 2; ++k) dst[n][k] = *(const PG8_LAS bf16x8*)(lds + PG8_SB(b, h) + boff + n * 2048 + k * 1024); } while (0)
; #define PG8_MMA(ai, bj, At, Bt) do { __builtin_amdgcn_s_setprio(1); _Pragma("unroll") for (int m = 0; m < 4; ++m) _Pragma("unroll") for (int n = 0; n < 2; ++n) _Pragma("unroll") for (int k = 0; k < 2; ++k) \
;         acc[ai][bj][m][n] = __builtin_amdgcn_mfma_f32_16x16x32_bf16(Bt[n][k], At[m][k], acc[ai][bj][m][n], 0, 0, 0); __builtin_amdgcn_s_setprio(0); } while (0)
; #define PG8_WAIT_V(n) asm volatile("s_waitcnt vmcnt(" #n ")" ::: "memory")
; #define PG8_WAIT_L(n) asm volatile("s_waitcnt lgkmcnt(" #n ")" ::: "memory")
; #define PG8_BAR __builtin_amdgcn_s_barrier()
; #define PG8_SCHED __builtin_amdgcn_sched_barrier(0)
; template <class Epi, class Sched, bool ALIGN_EPI = false, bool SP2 = false>
; __device__ __forceinline__ void gemm_phase(PG8_LAS unsigned char* lds, const Gemm g, const Sched& S, const Epi& E) {
;     ...
;             PG8_WAIT_V(8); PG8_WAIT_L(0); PG8_BAR; PG8_MMA(1, 0, At, B0); PG8_MMA(1, 1, At, B1); PG8_BAR; PG8_SCHED;
;             PG8_LDB(B0, 1, 0); PG8_LDB(B1, 1, 1); PG8_SCHED; PG8_LDA(At, 1, 0); PG8_STAGE(PG8_SA(0, 1), a2 + hstep, voffA);
;             PG8_WAIT_V(8); PG8_WAIT_L(0); PG8_BAR; PG8_MMA(0, 0, At, B0); PG8_MMA(0, 1, At, B1); PG8_BAR; PG8_SCHED;
	v_mfma_f32_16x16x32_bf16 v[60:63], v[144:147], v[196:199], v[60:63]
	v_mfma_f32_16x16x32_bf16 v[56:59], v[172:175], v[196:199], v[56:59]
	v_mfma_f32_16x16x32_bf16 v[52:55], v[144:147], v[204:207], v[52:55]
	v_mfma_f32_16x16x32_bf16 v[44:47], v[172:175], v[204:207], v[44:47]
	v_mfma_f32_16x16x32_bf16 v[36:39], v[144:147], v[212:215], v[36:39]
	v_mfma_f32_16x16x32_bf16 v[28:31], v[172:175], v[212:215], v[28:31]
	v_mfma_f32_16x16x32_bf16 v[20:23], v[144:147], v[220:223], v[20:23]
	v_mfma_f32_16x16x32_bf16 v[12:15], v[172:175], v[220:223], v[12:15]
	v_mfma_f32_16x16x32_bf16 v[60:63], v[164:167], v[200:203], v[60:63]
	v_mfma_f32_16x16x32_bf16 v[56:59], v[176:179], v[200:203], v[56:59]
	v_mfma_f32_16x16x32_bf16 v[52:55], v[164:167], v[208:211], v[52:55]
	v_mfma_f32_16x16x32_bf16 v[44:47], v[176:179], v[208:211], v[44:47]
	v_mfma_f32_16x16x32_bf16 v[36:39], v[164:167], v[216:219], v[36:39]
	v_mfma_f32_16x16x32_bf16 v[28:31], v[176:179], v[216:219], v[28:31]
	v_mfma_f32_16x16x32_bf16 v[20:23], v[164:167], v[224:227], v[20:23]
	v_mfma_f32_16x16x32_bf16 v[12:15], v[176:179], v[224:227], v[12:15]
	s_setprio 0
	s_setprio 1
	v_mfma_f32_16x16x32_bf16 v[48:51], v[180:183], v[196:199], v[48:51]
	v_mfma_f32_16x16x32_bf16 v[40:43], v[188:191], v[196:199], v[40:43]
	v_mfma_f32_16x16x32_bf16 v[32:35], v[180:183], v[204:207], v[32:35]
	v_mfma_f32_16x16x32_bf16 v[24:27], v[188:191], v[204:207], v[24:27]
	v_mfma_f32_16x16x32_bf16 v[16:19], v[180:183], v[212:215], v[16:19]
	v_mfma_f32_16x16x32_bf16 v[8:11], v[188:191], v[212:215], v[8:11]
	v_mfma_f32_16x16x32_bf16 v[4:7], v[180:183], v[220:223], v[4:7]
	v_mfma_f32_16x16x32_bf16 v[0:3], v[188:191], v[220:223], v[0:3]
	v_mfma_f32_16x16x32_bf16 v[48:51], v[184:187], v[200:203], v[48:51]
	v_mfma_f32_16x16x32_bf16 v[40:43], v[192:195], v[200:203], v[40:43]
	v_mfma_f32_16x16x32_bf16 v[32:35], v[184:187], v[208:211], v[32:35]
	v_mfma_f32_16x16x32_bf16 v[24:27], v[192:195], v[208:211], v[24:27]
	v_mfma_f32_16x16x32_bf16 v[16:19], v[184:187], v[216:219], v[16:19]
	v_mfma_f32_16x16x32_bf16 v[8:11], v[192:195], v[216:219], v[8:11]
	v_mfma_f32_16x16x32_bf16 v[4:7], v[184:187], v[224:227], v[4:7]
	v_mfma_f32_16x16x32_bf16 v[0:3], v[192:195], v[224:227], v[0:3]
	s_barrier
	s_setprio 0
	s_add_i32 s58, 0, 0x18000
	v_add_u32_e32 v163, s58, v158
	s_add_i32 s59, 0, 0x1c000
	ds_read_b128 v[144:147], v163
	ds_read_b128 v[164:167], v163 offset:1024
	ds_read_b128 v[172:175], v163 offset:2048
	ds_read_b128 v[176:179], v163 offset:3072
	v_add_u32_e32 v163, s59, v158
	ds_read_b128 v[180:183], v163
	ds_read_b128 v[184:187], v163 offset:1024
	ds_read_b128 v[188:191], v163 offset:2048
	ds_read_b128 v[192:195], v163 offset:3072
	s_add_u32 s36, s48, 0x80000
	s_addc_u32 s37, s49, 0
	s_mov_b32 m0, s54
	v_lshl_add_u64 v[234:235], s[36:37], 0, v[134:135]
	ds_read_b128 v[196:199], v162 offset:32768
	ds_read_b128 v[200:203], v162 offset:33792
	ds_read_b128 v[204:207], v162 offset:34816
	ds_read_b128 v[208:211], v162 offset:35840
	ds_read_b128 v[212:215], v162 offset:36864
	ds_read_b128 v[216:219], v162 offset:37888
	ds_read_b128 v[220:223], v162 offset:38912
	ds_read_b128 v[224:227], v162 offset:39936
	global_load_lds_dwordx4 v[234:235], off
	v_lshl_add_u64 v[234:235], s[36:37], 0, v[130:131]
	s_mov_b32 m0, s55
	s_nop 0
	global_load_lds_dwordx4 v[234:235], off
	s_waitcnt vmcnt(8)
	s_waitcnt lgkmcnt(0)
	s_setprio 1
	s_barrier
	v_mfma_f32_16x16x32_bf16 v[124:127], v[144:147], v[196:199], v[124:127]
	v_mfma_f32_16x16x32_bf16 v[120:123], v[172:175], v[196:199], v[120:123]
	v_mfma_f32_16x16x32_bf16 v[116:119], v[144:147], v[204:207], v[116:119]
	v_mfma_f32_16x16x32_bf16 v[108:111], v[172:175], v[204:207], v[108:111]
	v_mfma_f32_16x16x32_bf16 v[100:103], v[144:147], v[212:215], v[100:103]
	v_mfma_f32_16x16x32_bf16 v[92:95], v[172:175], v[212:215], v[92:95]
	v_mfma_f32_16x16x32_bf16 v[84:87], v[144:147], v[220:223], v[84:87]
	v_mfma_f32_16x16x32_bf16 v[76:79], v[172:175], v[220:223], v[76:79]
	v_mfma_f32_16x16x32_bf16 v[124:127], v[164:167], v[200:203], v[124:127]
	v_mfma_f32_16x16x32_bf16 v[120:123], v[176:179], v[200:203], v[120:123]
	v_mfma_f32_16x16x32_bf16 v[116:119], v[164:167], v[208:211], v[116:119]
	v_mfma_f32_16x16x32_bf16 v[108:111], v[176:179], v[208:211], v[108:111]
	v_mfma_f32_16x16x32_bf16 v[100:103], v[164:167], v[216:219], v[100:103]
	v_mfma_f32_16x16x32_bf16 v[92:95], v[176:179], v[216:219], v[92:95]
	v_mfma_f32_16x16x32_bf16 v[84:87], v[164:167], v[224:227], v[84:87]
	v_mfma_f32_16x16x32_bf16 v[76:79], v[176:179], v[224:227], v[76:79]
	s_setprio 0
	s_setprio 1
	v_mfma_f32_16x16x32_bf16 v[112:115], v[180:183], v[196:199], v[112:115]
	v_mfma_f32_16x16x32_bf16 v[104:107], v[188:191], v[196:199], v[104:107]
	v_mfma_f32_16x16x32_bf16 v[96:99], v[180:183], v[204:207], v[96:99]
	v_mfma_f32_16x16x32_bf16 v[88:91], v[188:191], v[204:207], v[88:91]
	v_mfma_f32_16x16x32_bf16 v[80:83], v[180:183], v[212:215], v[80:83]
	v_mfma_f32_16x16x32_bf16 v[72:75], v[188:191], v[212:215], v[72:75]
	v_mfma_f32_16x16x32_bf16 v[68:71], v[180:183], v[220:223], v[68:71]
	v_mfma_f32_16x16x32_bf16 v[64:67], v[188:191], v[220:223], v[64:67]
	v_mfma_f32_16x16x32_bf16 v[112:115], v[184:187], v[200:203], v[112:115]
	v_mfma_f32_16x16x32_bf16 v[104:107], v[192:195], v[200:203], v[104:107]
	v_mfma_f32_16x16x32_bf16 v[96:99], v[184:187], v[208:211], v[96:99]
	v_mfma_f32_16x16x32_bf16 v[88:91], v[192:195], v[208:211], v[88:91]
	v_mfma_f32_16x16x32_bf16 v[80:83], v[184:187], v[216:219], v[80:83]
	v_mfma_f32_16x16x32_bf16 v[72:75], v[192:195], v[216:219], v[72:75]
	v_mfma_f32_16x16x32_bf16 v[68:71], v[184:187], v[224:227], v[68:71]
	v_mfma_f32_16x16x32_bf16 v[64:67], v[192:195], v[224:227], v[64:67]
	s_barrier
; #define PG8_STAGE(bufoff, gbase, voff) do { _Pragma("unroll") for (int _i = 0; _i < 2; ++_i) \
;         __builtin_amdgcn_global_load_lds((const unsigned*)((const char*)(gbase) + (voff)[_i]), (PG8_LAS unsigned*)(lds + (bufoff) + ldsw + _i * 8192), 16, 0, 0); } while (0)
; #define PG8_LDA(dst, b, h) do { _Pragma("unroll") for (int m = 0; m < 4; ++m) _Pragma("unroll") for (int k = 0; k < 2; ++k) dst[m][k] = *(const PG8_LAS bf16x8*)(lds + PG8_SA(b, h) + aoff + m * 2048 + k * 1024); } while (0)
; #define PG8_MMA(ai, bj, At, Bt) do { __builtin_amdgcn_s_setprio(1); _Pragma("unroll") for (int m = 0; m < 4; ++m) _Pragma("unroll") for (int n = 0; n < 2; ++n) _Pragma("unroll") for (int k = 0; k < 2; ++k) \
;         acc[ai][bj][m][n] = __builtin_amdgcn_mfma_f32_16x16x32_bf16(Bt[n][k], At[m][k], acc[ai][bj][m][n], 0, 0, 0); __builtin_amdgcn_s_setprio(0); } while (0)
; #define PG8_WAIT_V(n) asm volatile("s_waitcnt vmcnt(" #n ")" ::: "memory")
; #define PG8_WAIT_L(n) asm volatile("s_waitcnt lgkmcnt(" #n ")" ::: "memory")
; #define PG8_BAR __builtin_amdgcn_s_barrier()
; #define PG8_SCHED __builtin_amdgcn_sched_barrier(0)
; template <class Epi, class Sched, bool ALIGN_EPI = false, bool SP2 = false>
; __device__ __forceinline__ void gemm_phase(PG8_LAS unsigned char* lds, const Gemm g, const Sched& S, const Epi& E) {
;     ...
;             PG8_LDA(At, 1, 1); PG8_STAGE(PG8_SB(1, 0), b3, voffB); PG8_STAGE(PG8_SB(1, 1), b3 + hstep, voffB); PG8_STAGE(PG8_SA(1, 0), a3, voffA);
;             PG8_WAIT_V(8); PG8_WAIT_L(0); PG8_BAR; PG8_MMA(1, 0, At, B0); PG8_MMA(1, 1, At, B1); PG8_BAR; PG8_SCHED;
;     ...
;         }
;         if constexpr (ALIGN_EPI) { if (wr == 0) PG8_BAR; }
	s_setprio 0
	s_add_i32 s36, s58, s3
	v_lshl_add_u64 v[168:169], v[168:169], 0, s[12:13]
	s_mov_b32 m0, s36
	ds_read_b128 v[196:199], v162 offset:49152
	ds_read_b128 v[200:203], v162 offset:50176
	ds_read_b128 v[204:207], v162 offset:51200
	ds_read_b128 v[208:211], v162 offset:52224
	ds_read_b128 v[212:215], v162 offset:53248
	ds_read_b128 v[216:219], v162 offset:54272
	ds_read_b128 v[220:223], v162 offset:55296
	ds_read_b128 v[224:227], v162 offset:56320
	global_load_lds_dwordx4 v[168:169], off
	s_add_i32 m0, s36, 0x2000
	s_add_u32 s34, s34, 0x80080
	v_lshl_add_u64 v[168:169], v[228:229], 0, s[12:13]
	s_addc_u32 s35, s35, 0
	s_add_i32 s36, s59, s3
	global_load_lds_dwordx4 v[168:169], off
	v_lshl_add_u64 v[168:169], s[34:35], 0, v[132:133]
	s_mov_b32 m0, s36
	s_nop 0
	global_load_lds_dwordx4 v[168:169], off
	v_lshl_add_u64 v[168:169], s[34:35], 0, v[128:129]
	s_add_i32 m0, s36, 0x2000
	s_nop 0
	global_load_lds_dwordx4 v[168:169], off
	v_lshl_add_u64 v[168:169], v[230:231], 0, s[12:13]
	s_mov_b32 m0, s68
	s_nop 0
	global_load_lds_dwordx4 v[168:169], off
	v_lshl_add_u64 v[168:169], v[232:233], 0, s[12:13]
	s_mov_b32 m0, s69
	s_nop 0
	global_load_lds_dwordx4 v[168:169], off
	s_waitcnt vmcnt(8)
	s_waitcnt lgkmcnt(0)
	s_setprio 1
	s_barrier
	v_mfma_f32_16x16x32_bf16 v[60:63], v[144:147], v[196:199], v[60:63]
	v_mfma_f32_16x16x32_bf16 v[56:59], v[172:175], v[196:199], v[56:59]
	v_mfma_f32_16x16x32_bf16 v[52:55], v[144:147], v[204:207], v[52:55]
	v_mfma_f32_16x16x32_bf16 v[44:47], v[172:175], v[204:207], v[44:47]
	v_mfma_f32_16x16x32_bf16 v[36:39], v[144:147], v[212:215], v[36:39]
	v_mfma_f32_16x16x32_bf16 v[28:31], v[172:175], v[212:215], v[28:31]
	v_mfma_f32_16x16x32_bf16 v[20:23], v[144:147], v[220:223], v[20:23]
	v_mfma_f32_16x16x32_bf16 v[12:15], v[172:175], v[220:223], v[12:15]
	v_mfma_f32_16x16x32_bf16 v[60:63], v[164:167], v[200:203], v[60:63]
	v_mfma_f32_16x16x32_bf16 v[56:59], v[176:179], v[200:203], v[56:59]
	v_mfma_f32_16x16x32_bf16 v[52:55], v[164:167], v[208:211], v[52:55]
	v_mfma_f32_16x16x32_bf16 v[44:47], v[176:179], v[208:211], v[44:47]
	v_mfma_f32_16x16x32_bf16 v[36:39], v[164:167], v[216:219], v[36:39]
	v_mfma_f32_16x16x32_bf16 v[28:31], v[176:179], v[216:219], v[28:31]
	v_mfma_f32_16x16x32_bf16 v[20:23], v[164:167], v[224:227], v[20:23]
	v_mfma_f32_16x16x32_bf16 v[12:15], v[176:179], v[224:227], v[12:15]
	s_setprio 0
	s_setprio 1
	v_mfma_f32_16x16x32_bf16 v[48:51], v[180:183], v[196:199], v[48:51]
	v_mfma_f32_16x16x32_bf16 v[40:43], v[188:191], v[196:199], v[40:43]
	v_mfma_f32_16x16x32_bf16 v[32:35], v[180:183], v[204:207], v[32:35]
	v_mfma_f32_16x16x32_bf16 v[24:27], v[188:191], v[204:207], v[24:27]
	v_mfma_f32_16x16x32_bf16 v[16:19], v[180:183], v[212:215], v[16:19]
	v_mfma_f32_16x16x32_bf16 v[8:11], v[188:191], v[212:215], v[8:11]
	v_mfma_f32_16x16x32_bf16 v[4:7], v[180:183], v[220:223], v[4:7]
	v_mfma_f32_16x16x32_bf16 v[0:3], v[188:191], v[220:223], v[0:3]
	v_mfma_f32_16x16x32_bf16 v[48:51], v[184:187], v[200:203], v[48:51]
	v_mfma_f32_16x16x32_bf16 v[40:43], v[192:195], v[200:203], v[40:43]
	v_mfma_f32_16x16x32_bf16 v[32:35], v[184:187], v[208:211], v[32:35]
	v_mfma_f32_16x16x32_bf16 v[24:27], v[192:195], v[208:211], v[24:27]
	v_mfma_f32_16x16x32_bf16 v[16:19], v[184:187], v[216:219], v[16:19]
	v_mfma_f32_16x16x32_bf16 v[8:11], v[192:195], v[216:219], v[8:11]
	v_mfma_f32_16x16x32_bf16 v[4:7], v[184:187], v[224:227], v[4:7]
	v_mfma_f32_16x16x32_bf16 v[0:3], v[192:195], v[224:227], v[0:3]
	s_barrier
	s_setprio 0
	s_add_i32 s84, s84, 2
	s_add_u32 s30, s30, 0x100
	s_addc_u32 s31, s31, 0
	s_add_u32 s82, s82, 0x100
	s_addc_u32 s83, s83, 0
	s_cmp_gt_u32 s84, 29
	s_cbranch_scc0 .LBB0_139
	s_and_b64 vcc, exec, s[14:15]
	s_cbranch_vccz .LBB0_142
	s_barrier

; #define PG8_STAGE(bufoff, gbase, voff) do { _Pragma("unroll") for (int _i = 0; _i < 2; ++_i) \
;         __builtin_amdgcn_global_load_lds((const unsigned*)((const char*)(gbase) + (voff)[_i]), (PG8_LAS unsigned*)(lds + (bufoff) + ldsw + _i * 8192), 16, 0, 0); } while (0)
; #define PG8_LDA(dst, b, h) do { _Pragma("unroll") for (int m = 0; m < 4; ++m) _Pragma("unroll") for (int k = 0; k < 2; ++k) dst[m][k] = *(const PG8_LAS bf16x8*)(lds + PG8_SA(b, h) + aoff + m * 2048 + k * 1024); } while (0)
; #define PG8_LDB(dst, b, h) do { _Pragma("unroll") for (int n = 0; n < 2; ++n) _Pragma("unroll") for (int k = 0; k < 2; ++k) dst[n][k] = *(const PG8_LAS bf16x8*)(lds + PG8_SB(b, h) + boff + n * 2048 + k * 1024); } while (0)
; #define PG8_MMA(ai, bj, At, Bt) do { __builtin_amdgcn_s_setprio(1); _Pragma("unroll") for (int m = 0; m < 4; ++m) _Pragma("unroll") for (int n = 0; n < 2; ++n) _Pragma("unroll") for (int k = 0; k < 2; ++k) \
;         acc[ai][bj][m][n] = __builtin_amdgcn_mfma_f32_16x16x32_bf16(Bt[n][k], At[m][k], acc[ai][bj][m][n], 0, 0, 0); __builtin_amdgcn_s_setprio(0); } while (0)
; #define PG8_WAIT_V(n) asm volatile("s_waitcnt vmcnt(" #n ")" ::: "memory")
; #define PG8_WAIT_L(n) asm volatile("s_waitcnt lgkmcnt(" #n ")" ::: "memory")
; template <class Epi, class Sched, bool ALIGN_EPI = false, bool SP2 = false>
; __device__ __forceinline__ void gemm_phase(PG8_LAS unsigned char* lds, const Gemm g, const Sched& S, const Epi& E) {
;     ...
;             const bool last = (t == nt - 2);
;             const char* a1 = cA + (size_t)(t + 1) * kstep;
;             const char* a2 = last ? nA : cA + (size_t)(t + 2) * kstep; const char* b2 = last ? nB : cB + (size_t)(t + 2) * kstep;
;             const char* a3 = a2 + kstep; const char* b3 = b2 + kstep;
;             if (last && has_next) S.a_ready(nxt);
;             if constexpr (SP2) {
;             PG8_LDB(B0, 0, 0); PG8_LDB(B1, 0, 1); PG8_SCHED; PG8_LDA(At, 0, 0); PG8_STAGE(PG8_SA(1, 1), a1 + hstep, voffA);
;             PG8_WAIT_V(8); PG8_WAIT_L(0); PG8_BAR; PG8_MMA(0, 0, At, B0); PG8_MMA(0, 1, At, B1); PG8_BAR; PG8_SCHED;
;             PG8_LDA(At, 0, 1); PG8_STAGE(PG8_SB(0, 0), b2, voffB); PG8_STAGE(PG8_SB(0, 1), b2 + hstep, voffB); PG8_STAGE(PG8_SA(0, 0), a2, voffA);
;             PG8_WAIT_V(8); PG8_WAIT_L(0); PG8_BAR; PG8_MMA(1, 0, At, B0); PG8_MMA(1, 1, At, B1); PG8_BAR; PG8_SCHED;
.LBB0_163:
	s_add_u32 s29, s34, s52
	s_addc_u32 s53, s35, 0
	s_add_u32 s54, s29, 0x100
	s_addc_u32 s55, s53, 0
	s_and_b64 s[36:37], s[50:51], exec
	s_cselect_b32 s55, s23, s55
	s_cselect_b32 s54, s90, s54
	s_add_u32 s36, s30, s52
	s_addc_u32 s37, s31, 0
	s_add_u32 s52, s36, 0x100
	s_addc_u32 s59, s37, 0
	s_and_b64 s[36:37], s[50:51], exec
	s_cselect_b32 s69, s21, s59
	s_cselect_b32 s68, s91, s52
	s_add_u32 s76, s29, 0x10080
	ds_read_b128 v[148:151], v145
	ds_read_b128 v[152:155], v145 offset:1024
	ds_read_b128 v[156:159], v145 offset:2048
	ds_read_b128 v[160:163], v145 offset:3072
	ds_read_b128 v[164:167], v146
	ds_read_b128 v[172:175], v146 offset:1024
	ds_read_b128 v[176:179], v146 offset:2048
	ds_read_b128 v[180:183], v146 offset:3072
	s_addc_u32 s77, s53, 0
	s_add_i32 s37, s87, s39
	s_add_i32 m0, s58, 0xc000
	s_add_i32 s29, s58, 0xe000
	s_add_i32 vcc_lo, s37, 0x2000
	s_add_u32 s74, s68, 0x10000
	s_addc_u32 s75, s69, 0
	s_add_i32 vcc_hi, s88, s39
	s_add_i32 s36, vcc_hi, 0x2000
	s_add_i32 s97, 0, 0x18000
	s_add_i32 s96, 0, 0x1c000
	s_add_u32 s52, s54, 0x10000
	s_addc_u32 s53, s55, 0
	s_add_i32 s95, s97, s39
	s_add_i32 s93, s95, 0x2000
	s_add_u32 s50, s68, 0x10080
	s_addc_u32 s51, s69, 0
	s_add_i32 s94, s96, s39
	s_add_i32 s92, s94, 0x2000
	v_lshl_add_u64 v[140:141], s[76:77], 0, v[128:129]
	ds_read_b128 v[184:187], v147
	ds_read_b128 v[188:191], v147 offset:1024
	ds_read_b128 v[192:195], v147 offset:2048
	ds_read_b128 v[196:199], v147 offset:3072
	ds_read_b128 v[200:203], v147 offset:4096
	ds_read_b128 v[204:207], v147 offset:5120
	ds_read_b128 v[208:211], v147 offset:6144
	ds_read_b128 v[212:215], v147 offset:7168
	global_load_lds_dwordx4 v[140:141], off
	v_lshl_add_u64 v[140:141], s[76:77], 0, v[132:133]
	s_mov_b32 m0, s29
	s_nop 0
	global_load_lds_dwordx4 v[140:141], off
	s_waitcnt vmcnt(8)
	s_waitcnt lgkmcnt(0)
	s_setprio 1
	s_barrier
	v_mfma_f32_16x16x32_bf16 v[124:127], v[148:151], v[184:187], v[124:127]
	v_mfma_f32_16x16x32_bf16 v[120:123], v[156:159], v[184:187], v[120:123]
	v_mfma_f32_16x16x32_bf16 v[116:119], v[148:151], v[192:195], v[116:119]
	v_mfma_f32_16x16x32_bf16 v[108:111], v[156:159], v[192:195], v[108:111]
	v_mfma_f32_16x16x32_bf16 v[100:103], v[148:151], v[200:203], v[100:103]
	v_mfma_f32_16x16x32_bf16 v[92:95], v[156:159], v[200:203], v[92:95]
	v_mfma_f32_16x16x32_bf16 v[84:87], v[148:151], v[208:211], v[84:87]
	v_mfma_f32_16x16x32_bf16 v[76:79], v[156:159], v[208:211], v[76:79]
	v_mfma_f32_16x16x32_bf16 v[124:127], v[152:155], v[188:191], v[124:127]
	v_mfma_f32_16x16x32_bf16 v[120:123], v[160:163], v[188:191], v[120:123]
	v_mfma_f32_16x16x32_bf16 v[116:119], v[152:155], v[196:199], v[116:119]
	v_mfma_f32_16x16x32_bf16 v[108:111], v[160:163], v[196:199], v[108:111]
	v_mfma_f32_16x16x32_bf16 v[100:103], v[152:155], v[204:207], v[100:103]
	v_mfma_f32_16x16x32_bf16 v[92:95], v[160:163], v[204:207], v[92:95]
	v_mfma_f32_16x16x32_bf16 v[84:87], v[152:155], v[212:215], v[84:87]
	v_mfma_f32_16x16x32_bf16 v[76:79], v[160:163], v[212:215], v[76:79]
	s_setprio 0
	s_setprio 1
	v_mfma_f32_16x16x32_bf16 v[112:115], v[164:167], v[184:187], v[112:115]
	v_mfma_f32_16x16x32_bf16 v[104:107], v[176:179], v[184:187], v[104:107]
	v_mfma_f32_16x16x32_bf16 v[96:99], v[164:167], v[192:195], v[96:99]
	v_mfma_f32_16x16x32_bf16 v[88:91], v[176:179], v[192:195], v[88:91]
	v_mfma_f32_16x16x32_bf16 v[80:83], v[164:167], v[200:203], v[80:83]
	v_mfma_f32_16x16x32_bf16 v[72:75], v[176:179], v[200:203], v[72:75]
	v_mfma_f32_16x16x32_bf16 v[68:71], v[164:167], v[208:211], v[68:71]
	v_mfma_f32_16x16x32_bf16 v[64:67], v[176:179], v[208:211], v[64:67]
	v_mfma_f32_16x16x32_bf16 v[112:115], v[172:175], v[188:191], v[112:115]
	v_mfma_f32_16x16x32_bf16 v[104:107], v[180:183], v[188:191], v[104:107]
	v_mfma_f32_16x16x32_bf16 v[96:99], v[172:175], v[196:199], v[96:99]
	v_mfma_f32_16x16x32_bf16 v[88:91], v[180:183], v[196:199], v[88:91]
	v_mfma_f32_16x16x32_bf16 v[80:83], v[172:175], v[204:207], v[80:83]
	v_mfma_f32_16x16x32_bf16 v[72:75], v[180:183], v[204:207], v[72:75]
	v_mfma_f32_16x16x32_bf16 v[68:71], v[172:175], v[212:215], v[68:71]
	v_mfma_f32_16x16x32_bf16 v[64:67], v[180:183], v[212:215], v[64:67]
	s_barrier
	s_setprio 0
	s_mov_b32 m0, s37
	v_lshl_add_u64 v[140:141], s[68:69], 0, v[130:131]
	ds_read_b128 v[184:187], v147 offset:16384
	ds_read_b128 v[188:191], v147 offset:17408
	ds_read_b128 v[192:195], v147 offset:18432
	ds_read_b128 v[196:199], v147 offset:19456
	ds_read_b128 v[200:203], v147 offset:20480
	ds_read_b128 v[204:207], v147 offset:21504
	ds_read_b128 v[208:211], v147 offset:22528
	ds_read_b128 v[212:215], v147 offset:23552
	global_load_lds_dwordx4 v[140:141], off
	v_lshl_add_u64 v[168:169], s[68:69], 0, v[134:135]
	s_mov_b32 m0, vcc_lo
	v_lshl_add_u64 v[216:217], s[74:75], 0, v[130:131]
	global_load_lds_dwordx4 v[168:169], off
	s_mov_b32 m0, vcc_hi
	v_lshl_add_u64 v[218:219], s[54:55], 0, v[132:133]
	global_load_lds_dwordx4 v[216:217], off
	v_lshl_add_u64 v[216:217], s[74:75], 0, v[134:135]
	s_mov_b32 m0, s36
	s_nop 0
	global_load_lds_dwordx4 v[216:217], off
	v_lshl_add_u64 v[216:217], s[54:55], 0, v[128:129]
	s_mov_b32 m0, s58
	s_nop 0
	global_load_lds_dwordx4 v[216:217], off
	s_mov_b32 m0, s79
	s_nop 0
	global_load_lds_dwordx4 v[218:219], off
	s_waitcnt vmcnt(8)
	s_waitcnt lgkmcnt(0)
	s_setprio 1
	s_barrier
; #define PG8_STAGE(bufoff, gbase, voff) do { _Pragma("unroll") for (int _i = 0; _i < 2; ++_i) \
;         __builtin_amdgcn_global_load_lds((const unsigned*)((const char*)(gbase) + (voff)[_i]), (PG8_LAS unsigned*)(lds + (bufoff) + ldsw + _i * 8192), 16, 0, 0); } while (0)
; #define PG8_LDA(dst, b, h) do { _Pragma("unroll") for (int m = 0; m < 4; ++m) _Pragma("unroll") for (int k = 0; k < 2; ++k) dst[m][k] = *(const PG8_LAS bf16x8*)(lds + PG8_SA(b, h) + aoff + m * 2048 + k * 1024); } while (0)
; #define PG8_LDB(dst, b, h) do { _Pragma("unroll") for (int n = 0; n < 2; ++n) _Pragma("unroll") for (int k = 0; k < 2; ++k) dst[n][k] = *(const PG8_LAS bf16x8*)(lds + PG8_SB(b, h) + boff + n * 2048 + k * 1024); } while (0)
; #define PG8_MMA(ai, bj, At, Bt) do { __builtin_amdgcn_s_setprio(1); _Pragma("unroll") for (int m = 0; m < 4; ++m) _Pragma("unroll") for (int n = 0; n < 2; ++n) _Pragma("unroll") for (int k = 0; k < 2; ++k) \
;         acc[ai][bj][m][n] = __builtin_amdgcn_mfma_f32_16x16x32_bf16(Bt[n][k], At[m][k], acc[ai][bj][m][n], 0, 0, 0); __builtin_amdgcn_s_setprio(0); } while (0)
; #define PG8_WAIT_V(n) asm volatile("s_waitcnt vmcnt(" #n ")" ::: "memory")
; #define PG8_WAIT_L(n) asm volatile("s_waitcnt lgkmcnt(" #n ")" ::: "memory")
; #define PG8_BAR __builtin_amdgcn_s_barrier()
; #define PG8_SCHED __builtin_amdgcn_sched_barrier(0)
; template <class Epi, class Sched, bool ALIGN_EPI = false, bool SP2 = false>
; __device__ __forceinline__ void gemm_phase(PG8_LAS unsigned char* lds, const Gemm g, const Sched& S, const Epi& E) {
;     ...
;             PG8_WAIT_V(8); PG8_WAIT_L(0); PG8_BAR; PG8_MMA(1, 0, At, B0); PG8_MMA(1, 1, At, B1); PG8_BAR; PG8_SCHED;
;             PG8_LDB(B0, 1, 0); PG8_LDB(B1, 1, 1); PG8_SCHED; PG8_LDA(At, 1, 0); PG8_STAGE(PG8_SA(0, 1), a2 + hstep, voffA);
;             PG8_WAIT_V(8); PG8_WAIT_L(0); PG8_BAR; PG8_MMA(0, 0, At, B0); PG8_MMA(0, 1, At, B1); PG8_BAR; PG8_SCHED;
	v_mfma_f32_16x16x32_bf16 v[60:63], v[148:151], v[184:187], v[60:63]
	v_mfma_f32_16x16x32_bf16 v[56:59], v[156:159], v[184:187], v[56:59]
	v_mfma_f32_16x16x32_bf16 v[52:55], v[148:151], v[192:195], v[52:55]
	v_mfma_f32_16x16x32_bf16 v[44:47], v[156:159], v[192:195], v[44:47]
	v_mfma_f32_16x16x32_bf16 v[36:39], v[148:151], v[200:203], v[36:39]
	v_mfma_f32_16x16x32_bf16 v[28:31], v[156:159], v[200:203], v[28:31]
	v_mfma_f32_16x16x32_bf16 v[20:23], v[148:151], v[208:211], v[20:23]
	v_mfma_f32_16x16x32_bf16 v[12:15], v[156:159], v[208:211], v[12:15]
	v_mfma_f32_16x16x32_bf16 v[60:63], v[152:155], v[188:191], v[60:63]
	v_mfma_f32_16x16x32_bf16 v[56:59], v[160:163], v[188:191], v[56:59]
	v_mfma_f32_16x16x32_bf16 v[52:55], v[152:155], v[196:199], v[52:55]
	v_mfma_f32_16x16x32_bf16 v[44:47], v[160:163], v[196:199], v[44:47]
	v_mfma_f32_16x16x32_bf16 v[36:39], v[152:155], v[204:207], v[36:39]
	v_mfma_f32_16x16x32_bf16 v[28:31], v[160:163], v[204:207], v[28:31]
	v_mfma_f32_16x16x32_bf16 v[20:23], v[152:155], v[212:215], v[20:23]
	v_mfma_f32_16x16x32_bf16 v[12:15], v[160:163], v[212:215], v[12:15]
	s_setprio 0
	s_setprio 1
	v_mfma_f32_16x16x32_bf16 v[48:51], v[164:167], v[184:187], v[48:51]
	v_mfma_f32_16x16x32_bf16 v[40:43], v[176:179], v[184:187], v[40:43]
	v_mfma_f32_16x16x32_bf16 v[32:35], v[164:167], v[192:195], v[32:35]
	v_mfma_f32_16x16x32_bf16 v[24:27], v[176:179], v[192:195], v[24:27]
	v_mfma_f32_16x16x32_bf16 v[16:19], v[164:167], v[200:203], v[16:19]
	v_mfma_f32_16x16x32_bf16 v[8:11], v[176:179], v[200:203], v[8:11]
	v_mfma_f32_16x16x32_bf16 v[4:7], v[164:167], v[208:211], v[4:7]
	v_mfma_f32_16x16x32_bf16 v[0:3], v[176:179], v[208:211], v[0:3]
	v_mfma_f32_16x16x32_bf16 v[48:51], v[172:175], v[188:191], v[48:51]
	v_mfma_f32_16x16x32_bf16 v[40:43], v[180:183], v[188:191], v[40:43]
	v_mfma_f32_16x16x32_bf16 v[32:35], v[172:175], v[196:199], v[32:35]
	v_mfma_f32_16x16x32_bf16 v[24:27], v[180:183], v[196:199], v[24:27]
	v_mfma_f32_16x16x32_bf16 v[16:19], v[172:175], v[204:207], v[16:19]
	v_mfma_f32_16x16x32_bf16 v[8:11], v[180:183], v[204:207], v[8:11]
	v_mfma_f32_16x16x32_bf16 v[4:7], v[172:175], v[212:215], v[4:7]
	v_mfma_f32_16x16x32_bf16 v[0:3], v[180:183], v[212:215], v[0:3]
	s_barrier
	s_setprio 0
	v_add_u32_e32 v160, s97, v143
	v_add_u32_e32 v180, s96, v143
	ds_read_b128 v[148:151], v160
	ds_read_b128 v[152:155], v160 offset:1024
	ds_read_b128 v[156:159], v160 offset:2048
	ds_read_b128 v[160:163], v160 offset:3072
	ds_read_b128 v[164:167], v180
	ds_read_b128 v[172:175], v180 offset:1024
	ds_read_b128 v[176:179], v180 offset:2048
	ds_read_b128 v[180:183], v180 offset:3072
	s_mov_b32 m0, s80
	v_lshl_add_u64 v[220:221], s[52:53], 0, v[128:129]
	ds_read_b128 v[184:187], v147 offset:32768
	ds_read_b128 v[188:191], v147 offset:33792
	ds_read_b128 v[192:195], v147 offset:34816
	ds_read_b128 v[196:199], v147 offset:35840
	ds_read_b128 v[200:203], v147 offset:36864
	ds_read_b128 v[204:207], v147 offset:37888
	ds_read_b128 v[208:211], v147 offset:38912
	ds_read_b128 v[212:215], v147 offset:39936
	global_load_lds_dwordx4 v[220:221], off
	v_lshl_add_u64 v[220:221], s[52:53], 0, v[132:133]
	s_mov_b32 m0, s81
	s_nop 0
	global_load_lds_dwordx4 v[220:221], off
	s_waitcnt vmcnt(8)
	s_waitcnt lgkmcnt(0)
	s_setprio 1
	s_barrier
	v_mfma_f32_16x16x32_bf16 v[124:127], v[148:151], v[184:187], v[124:127]
	v_mfma_f32_16x16x32_bf16 v[120:123], v[156:159], v[184:187], v[120:123]
	v_mfma_f32_16x16x32_bf16 v[116:119], v[148:151], v[192:195], v[116:119]
	v_mfma_f32_16x16x32_bf16 v[108:111], v[156:159], v[192:195], v[108:111]
	v_mfma_f32_16x16x32_bf16 v[100:103], v[148:151], v[200:203], v[100:103]
	v_mfma_f32_16x16x32_bf16 v[92:95], v[156:159], v[200:203], v[92:95]
	v_mfma_f32_16x16x32_bf16 v[84:87], v[148:151], v[208:211], v[84:87]
	v_mfma_f32_16x16x32_bf16 v[76:79], v[156:159], v[208:211], v[76:79]
	v_mfma_f32_16x16x32_bf16 v[124:127], v[152:155], v[188:191], v[124:127]
	v_mfma_f32_16x16x32_bf16 v[120:123], v[160:163], v[188:191], v[120:123]
	v_mfma_f32_16x16x32_bf16 v[116:119], v[152:155], v[196:199], v[116:119]
	v_mfma_f32_16x16x32_bf16 v[108:111], v[160:163], v[196:199], v[108:111]
	v_mfma_f32_16x16x32_bf16 v[100:103], v[152:155], v[204:207], v[100:103]
	v_mfma_f32_16x16x32_bf16 v[92:95], v[160:163], v[204:207], v[92:95]
	v_mfma_f32_16x16x32_bf16 v[84:87], v[152:155], v[212:215], v[84:87]
	v_mfma_f32_16x16x32_bf16 v[76:79], v[160:163], v[212:215], v[76:79]
	s_setprio 0
	s_setprio 1
	v_mfma_f32_16x16x32_bf16 v[112:115], v[164:167], v[184:187], v[112:115]
	v_mfma_f32_16x16x32_bf16 v[104:107], v[176:179], v[184:187], v[104:107]
	v_mfma_f32_16x16x32_bf16 v[96:99], v[164:167], v[192:195], v[96:99]
	v_mfma_f32_16x16x32_bf16 v[88:91], v[176:179], v[192:195], v[88:91]
	v_mfma_f32_16x16x32_bf16 v[80:83], v[164:167], v[200:203], v[80:83]
	v_mfma_f32_16x16x32_bf16 v[72:75], v[176:179], v[200:203], v[72:75]
	v_mfma_f32_16x16x32_bf16 v[68:71], v[164:167], v[208:211], v[68:71]
	v_mfma_f32_16x16x32_bf16 v[64:67], v[176:179], v[208:211], v[64:67]
	v_mfma_f32_16x16x32_bf16 v[112:115], v[172:175], v[188:191], v[112:115]
	v_mfma_f32_16x16x32_bf16 v[104:107], v[180:183], v[188:191], v[104:107]
	v_mfma_f32_16x16x32_bf16 v[96:99], v[172:175], v[196:199], v[96:99]
	v_mfma_f32_16x16x32_bf16 v[88:91], v[180:183], v[196:199], v[88:91]
	v_mfma_f32_16x16x32_bf16 v[80:83], v[172:175], v[204:207], v[80:83]
	v_mfma_f32_16x16x32_bf16 v[72:75], v[180:183], v[204:207], v[72:75]
	v_mfma_f32_16x16x32_bf16 v[68:71], v[172:175], v[212:215], v[68:71]
	v_mfma_f32_16x16x32_bf16 v[64:67], v[180:183], v[212:215], v[64:67]
	s_barrier
; #define PG8_STAGE(bufoff, gbase, voff) do { _Pragma("unroll") for (int _i = 0; _i < 2; ++_i) \
;         __builtin_amdgcn_global_load_lds((const unsigned*)((const char*)(gbase) + (voff)[_i]), (PG8_LAS unsigned*)(lds + (bufoff) + ldsw + _i * 8192), 16, 0, 0); } while (0)
; #define PG8_LDA(dst, b, h) do { _Pragma("unroll") for (int m = 0; m < 4; ++m) _Pragma("unroll") for (int k = 0; k < 2; ++k) dst[m][k] = *(const PG8_LAS bf16x8*)(lds + PG8_SA(b, h) + aoff + m * 2048 + k * 1024); } while (0)
; #define PG8_MMA(ai, bj, At, Bt) do { __builtin_amdgcn_s_setprio(1); _Pragma("unroll") for (int m = 0; m < 4; ++m) _Pragma("unroll") for (int n = 0; n < 2; ++n) _Pragma("unroll") for (int k = 0; k < 2; ++k) \
;         acc[ai][bj][m][n] = __builtin_amdgcn_mfma_f32_16x16x32_bf16(Bt[n][k], At[m][k], acc[ai][bj][m][n], 0, 0, 0); __builtin_amdgcn_s_setprio(0); } while (0)
; #define PG8_WAIT_V(n) asm volatile("s_waitcnt vmcnt(" #n ")" ::: "memory")
; #define PG8_WAIT_L(n) asm volatile("s_waitcnt lgkmcnt(" #n ")" ::: "memory")
; #define PG8_BAR __builtin_amdgcn_s_barrier()
; #define PG8_SCHED __builtin_amdgcn_sched_barrier(0)
; template <class Epi, class Sched, bool ALIGN_EPI = false, bool SP2 = false>
; __device__ __forceinline__ void gemm_phase(PG8_LAS unsigned char* lds, const Gemm g, const Sched& S, const Epi& E) {
;     ...
;             PG8_LDA(At, 1, 1); PG8_STAGE(PG8_SB(1, 0), b3, voffB); PG8_STAGE(PG8_SB(1, 1), b3 + hstep, voffB); PG8_STAGE(PG8_SA(1, 0), a3, voffA);
;             PG8_WAIT_V(8); PG8_WAIT_L(0); PG8_BAR; PG8_MMA(1, 0, At, B0); PG8_MMA(1, 1, At, B1); PG8_BAR; PG8_SCHED;
	s_setprio 0
	s_mov_b32 m0, s95
	v_lshl_add_u64 v[140:141], v[140:141], 0, s[12:13]
	ds_read_b128 v[184:187], v147 offset:49152
	ds_read_b128 v[188:191], v147 offset:50176
	ds_read_b128 v[192:195], v147 offset:51200
	ds_read_b128 v[196:199], v147 offset:52224
	ds_read_b128 v[200:203], v147 offset:53248
	ds_read_b128 v[204:207], v147 offset:54272
	ds_read_b128 v[208:211], v147 offset:55296
	ds_read_b128 v[212:215], v147 offset:56320
	global_load_lds_dwordx4 v[140:141], off
	v_lshl_add_u64 v[140:141], v[168:169], 0, s[12:13]
	s_mov_b32 m0, s93
	s_nop 0
	global_load_lds_dwordx4 v[140:141], off
	v_lshl_add_u64 v[140:141], s[50:51], 0, v[130:131]
	s_mov_b32 m0, s94
	s_nop 0
	global_load_lds_dwordx4 v[140:141], off
	v_lshl_add_u64 v[140:141], s[50:51], 0, v[134:135]
	s_mov_b32 m0, s92
	s_nop 0
	global_load_lds_dwordx4 v[140:141], off
	v_lshl_add_u64 v[140:141], v[216:217], 0, s[12:13]
	s_mov_b32 m0, s83
	s_nop 0
	global_load_lds_dwordx4 v[140:141], off
	v_lshl_add_u64 v[140:141], v[218:219], 0, s[12:13]
	s_mov_b32 m0, s84
	s_nop 0
	global_load_lds_dwordx4 v[140:141], off
	s_waitcnt vmcnt(8)
	s_waitcnt lgkmcnt(0)
	s_setprio 1
	s_barrier
	v_mfma_f32_16x16x32_bf16 v[60:63], v[148:151], v[184:187], v[60:63]
	v_mfma_f32_16x16x32_bf16 v[56:59], v[156:159], v[184:187], v[56:59]
	v_mfma_f32_16x16x32_bf16 v[52:55], v[148:151], v[192:195], v[52:55]
	v_mfma_f32_16x16x32_bf16 v[44:47], v[156:159], v[192:195], v[44:47]
	v_mfma_f32_16x16x32_bf16 v[36:39], v[148:151], v[200:203], v[36:39]
	v_mfma_f32_16x16x32_bf16 v[28:31], v[156:159], v[200:203], v[28:31]
	v_mfma_f32_16x16x32_bf16 v[20:23], v[148:151], v[208:211], v[20:23]
	v_mfma_f32_16x16x32_bf16 v[12:15], v[156:159], v[208:211], v[12:15]
	v_mfma_f32_16x16x32_bf16 v[60:63], v[152:155], v[188:191], v[60:63]
	v_mfma_f32_16x16x32_bf16 v[56:59], v[160:163], v[188:191], v[56:59]
	v_mfma_f32_16x16x32_bf16 v[52:55], v[152:155], v[196:199], v[52:55]
	v_mfma_f32_16x16x32_bf16 v[44:47], v[160:163], v[196:199], v[44:47]
	v_mfma_f32_16x16x32_bf16 v[36:39], v[152:155], v[204:207], v[36:39]
	v_mfma_f32_16x16x32_bf16 v[28:31], v[160:163], v[204:207], v[28:31]
	v_mfma_f32_16x16x32_bf16 v[20:23], v[152:155], v[212:215], v[20:23]
	v_mfma_f32_16x16x32_bf16 v[12:15], v[160:163], v[212:215], v[12:15]
	s_setprio 0
	s_setprio 1
	v_mfma_f32_16x16x32_bf16 v[48:51], v[164:167], v[184:187], v[48:51]
	v_mfma_f32_16x16x32_bf16 v[40:43], v[176:179], v[184:187], v[40:43]
	v_mfma_f32_16x16x32_bf16 v[32:35], v[164:167], v[192:195], v[32:35]
	v_mfma_f32_16x16x32_bf16 v[24:27], v[176:179], v[192:195], v[24:27]
	v_mfma_f32_16x16x32_bf16 v[16:19], v[164:167], v[200:203], v[16:19]
	v_mfma_f32_16x16x32_bf16 v[8:11], v[176:179], v[200:203], v[8:11]
	v_mfma_f32_16x16x32_bf16 v[4:7], v[164:167], v[208:211], v[4:7]
	v_mfma_f32_16x16x32_bf16 v[0:3], v[176:179], v[208:211], v[0:3]
	v_mfma_f32_16x16x32_bf16 v[48:51], v[172:175], v[188:191], v[48:51]
	v_mfma_f32_16x16x32_bf16 v[40:43], v[180:183], v[188:191], v[40:43]
	v_mfma_f32_16x16x32_bf16 v[32:35], v[172:175], v[196:199], v[32:35]
	v_mfma_f32_16x16x32_bf16 v[24:27], v[180:183], v[196:199], v[24:27]
	v_mfma_f32_16x16x32_bf16 v[16:19], v[172:175], v[204:207], v[16:19]
	v_mfma_f32_16x16x32_bf16 v[8:11], v[180:183], v[204:207], v[8:11]
	v_mfma_f32_16x16x32_bf16 v[4:7], v[172:175], v[212:215], v[4:7]
	v_mfma_f32_16x16x32_bf16 v[0:3], v[180:183], v[212:215], v[0:3]
	s_barrier
	s_setprio 0
	s_movk_i32 s52, 0x100
	s_andn2_b64 vcc, exec, s[48:49]
	s_mov_b64 s[50:51], -1
	s_mov_b64 s[48:49], 0
	s_cbranch_vccz .LBB0_163
	s_and_b64 vcc, exec, s[14:15]
	s_cbranch_vccz .LBB0_166
	s_barrier

; #define PG8_STAGE(bufoff, gbase, voff) do { _Pragma("unroll") for (int _i = 0; _i < 2; ++_i) \
;         __builtin_amdgcn_global_load_lds((const unsigned*)((const char*)(gbase) + (voff)[_i]), (PG8_LAS unsigned*)(lds + (bufoff) + ldsw + _i * 8192), 16, 0, 0); } while (0)
; #define PG8_LDA(dst, b, h) do { _Pragma("unroll") for (int m = 0; m < 4; ++m) _Pragma("unroll") for (int k = 0; k < 2; ++k) dst[m][k] = *(const PG8_LAS bf16x8*)(lds + PG8_SA(b, h) + aoff + m * 2048 + k * 1024); } while (0)
; #define PG8_LDB(dst, b, h) do { _Pragma("unroll") for (int n = 0; n < 2; ++n) _Pragma("unroll") for (int k = 0; k < 2; ++k) dst[n][k] = *(const PG8_LAS bf16x8*)(lds + PG8_SB(b, h) + boff + n * 2048 + k * 1024); } while (0)
; #define PG8_MMA(ai, bj, At, Bt) do { __builtin_amdgcn_s_setprio(1); _Pragma("unroll") for (int m = 0; m < 4; ++m) _Pragma("unroll") for (int n = 0; n < 2; ++n) _Pragma("unroll") for (int k = 0; k < 2; ++k) \
;         acc[ai][bj][m][n] = __builtin_amdgcn_mfma_f32_16x16x32_bf16(Bt[n][k], At[m][k], acc[ai][bj][m][n], 0, 0, 0); __builtin_amdgcn_s_setprio(0); } while (0)
; #define PG8_WAIT_V(n) asm volatile("s_waitcnt vmcnt(" #n ")" ::: "memory")
; #define PG8_WAIT_L(n) asm volatile("s_waitcnt lgkmcnt(" #n ")" ::: "memory")
; #define PG8_BAR __builtin_amdgcn_s_barrier()
; #define PG8_SCHED __builtin_amdgcn_sched_barrier(0)
; template <class Epi, class Sched, bool ALIGN_EPI = false, bool SP2 = false>
; __device__ __forceinline__ void gemm_phase(PG8_LAS unsigned char* lds, const Gemm g, const Sched& S, const Epi& E) {
;     ...
;             PG8_LDB(B0, 0, 0); PG8_LDB(B1, 0, 1); PG8_SCHED; PG8_LDA(At, 0, 0); PG8_STAGE(PG8_SA(1, 1), a1 + hstep, voffA);
;             PG8_WAIT_V(8); PG8_WAIT_L(0); PG8_BAR; PG8_MMA(0, 0, At, B0); PG8_MMA(0, 1, At, B1); PG8_BAR; PG8_SCHED;
;             PG8_LDA(At, 0, 1); PG8_STAGE(PG8_SB(0, 0), b2, voffB); PG8_STAGE(PG8_SB(0, 1), b2 + hstep, voffB); PG8_STAGE(PG8_SA(0, 0), a2, voffA);
;             PG8_WAIT_V(8); PG8_WAIT_L(0); PG8_BAR; PG8_MMA(1, 0, At, B0); PG8_MMA(1, 1, At, B1); PG8_BAR; PG8_SCHED;
.LBB0_393:
	ds_read_b128 v[146:149], v156
	ds_read_b128 v[150:153], v156 offset:1024
	ds_read_b128 v[160:163], v156 offset:2048
	ds_read_b128 v[164:167], v156 offset:3072
	ds_read_b128 v[172:175], v157
	ds_read_b128 v[176:179], v157 offset:1024
	ds_read_b128 v[180:183], v157 offset:2048
	ds_read_b128 v[184:187], v157 offset:3072
	s_add_u32 s34, s30, 0xfff80080
	s_addc_u32 s35, s31, -1
	s_cmp_eq_u32 s81, 28
	s_cselect_b32 s49, s23, s35
	s_cselect_b32 s48, s77, s34
	s_cselect_b32 s35, s21, s80
	s_cselect_b32 s34, s78, s79
	v_lshl_add_u64 v[168:169], s[30:31], 0, v[138:139]
	s_add_i32 m0, s29, 0xc000
	ds_read_b128 v[188:191], v158
	ds_read_b128 v[192:195], v158 offset:1024
	ds_read_b128 v[196:199], v158 offset:2048
	ds_read_b128 v[200:203], v158 offset:3072
	ds_read_b128 v[204:207], v158 offset:4096
	ds_read_b128 v[208:211], v158 offset:5120
	ds_read_b128 v[212:215], v158 offset:6144
	ds_read_b128 v[216:219], v158 offset:7168
	global_load_lds_dwordx4 v[168:169], off
	v_lshl_add_u64 v[168:169], s[30:31], 0, v[140:141]
	s_add_i32 m0, s29, 0xe000
	s_nop 0
	global_load_lds_dwordx4 v[168:169], off
	s_waitcnt vmcnt(8)
	s_waitcnt lgkmcnt(0)
	s_setprio 1
	s_barrier
	v_mfma_f32_16x16x32_bf16 v[124:127], v[146:149], v[188:191], v[124:127]
	v_mfma_f32_16x16x32_bf16 v[120:123], v[160:163], v[188:191], v[120:123]
	v_mfma_f32_16x16x32_bf16 v[116:119], v[146:149], v[196:199], v[116:119]
	v_mfma_f32_16x16x32_bf16 v[112:115], v[160:163], v[196:199], v[112:115]
	v_mfma_f32_16x16x32_bf16 v[108:111], v[146:149], v[204:207], v[108:111]
	v_mfma_f32_16x16x32_bf16 v[104:107], v[160:163], v[204:207], v[104:107]
	v_mfma_f32_16x16x32_bf16 v[100:103], v[146:149], v[212:215], v[100:103]
	v_mfma_f32_16x16x32_bf16 v[96:99], v[160:163], v[212:215], v[96:99]
	v_mfma_f32_16x16x32_bf16 v[124:127], v[150:153], v[192:195], v[124:127]
	v_mfma_f32_16x16x32_bf16 v[120:123], v[164:167], v[192:195], v[120:123]
	v_mfma_f32_16x16x32_bf16 v[116:119], v[150:153], v[200:203], v[116:119]
	v_mfma_f32_16x16x32_bf16 v[112:115], v[164:167], v[200:203], v[112:115]
	v_mfma_f32_16x16x32_bf16 v[108:111], v[150:153], v[208:211], v[108:111]
	v_mfma_f32_16x16x32_bf16 v[104:107], v[164:167], v[208:211], v[104:107]
	v_mfma_f32_16x16x32_bf16 v[100:103], v[150:153], v[216:219], v[100:103]
	v_mfma_f32_16x16x32_bf16 v[96:99], v[164:167], v[216:219], v[96:99]
	s_setprio 0
	s_setprio 1
	v_mfma_f32_16x16x32_bf16 v[60:63], v[172:175], v[188:191], v[60:63]
	v_mfma_f32_16x16x32_bf16 v[56:59], v[180:183], v[188:191], v[56:59]
	v_mfma_f32_16x16x32_bf16 v[52:55], v[172:175], v[196:199], v[52:55]
	v_mfma_f32_16x16x32_bf16 v[48:51], v[180:183], v[196:199], v[48:51]
	v_mfma_f32_16x16x32_bf16 v[44:47], v[172:175], v[204:207], v[44:47]
	v_mfma_f32_16x16x32_bf16 v[40:43], v[180:183], v[204:207], v[40:43]
	v_mfma_f32_16x16x32_bf16 v[36:39], v[172:175], v[212:215], v[36:39]
	v_mfma_f32_16x16x32_bf16 v[32:35], v[180:183], v[212:215], v[32:35]
	v_mfma_f32_16x16x32_bf16 v[60:63], v[176:179], v[192:195], v[60:63]
	v_mfma_f32_16x16x32_bf16 v[56:59], v[184:187], v[192:195], v[56:59]
	v_mfma_f32_16x16x32_bf16 v[52:55], v[176:179], v[200:203], v[52:55]
	v_mfma_f32_16x16x32_bf16 v[48:51], v[184:187], v[200:203], v[48:51]
	v_mfma_f32_16x16x32_bf16 v[44:47], v[176:179], v[208:211], v[44:47]
	v_mfma_f32_16x16x32_bf16 v[40:43], v[184:187], v[208:211], v[40:43]
	v_mfma_f32_16x16x32_bf16 v[36:39], v[176:179], v[216:219], v[36:39]
	v_mfma_f32_16x16x32_bf16 v[32:35], v[184:187], v[216:219], v[32:35]
	s_barrier
	s_setprio 0
	s_add_i32 s36, s74, s19
	v_lshl_add_u64 v[168:169], s[34:35], 0, v[130:131]
	s_mov_b32 m0, s36
	ds_read_b128 v[188:191], v158 offset:16384
	ds_read_b128 v[192:195], v158 offset:17408
	ds_read_b128 v[196:199], v158 offset:18432
	ds_read_b128 v[200:203], v158 offset:19456
	ds_read_b128 v[204:207], v158 offset:20480
	ds_read_b128 v[208:211], v158 offset:21504
	ds_read_b128 v[212:215], v158 offset:22528
	ds_read_b128 v[216:219], v158 offset:23552
	global_load_lds_dwordx4 v[168:169], off
	s_add_i32 m0, s36, 0x2000
	s_add_u32 s36, s34, 0x80000
	v_lshl_add_u64 v[220:221], s[34:35], 0, v[134:135]
	s_addc_u32 s37, s35, 0
	s_add_i32 s58, s75, s19
	global_load_lds_dwordx4 v[220:221], off
	v_lshl_add_u64 v[222:223], s[36:37], 0, v[130:131]
	s_mov_b32 m0, s58
	v_lshl_add_u64 v[224:225], s[48:49], 0, v[132:133]
	global_load_lds_dwordx4 v[222:223], off
	v_lshl_add_u64 v[222:223], s[36:37], 0, v[134:135]
	s_add_i32 m0, s58, 0x2000
	s_nop 0
	global_load_lds_dwordx4 v[222:223], off
	v_lshl_add_u64 v[222:223], s[48:49], 0, v[128:129]
	s_mov_b32 m0, s29
	s_nop 0
	global_load_lds_dwordx4 v[222:223], off
	s_mov_b32 m0, s39
	s_nop 0
	global_load_lds_dwordx4 v[224:225], off
	s_waitcnt vmcnt(8)
	s_waitcnt lgkmcnt(0)
	s_setprio 1
	s_barrier
; #define PG8_STAGE(bufoff, gbase, voff) do { _Pragma("unroll") for (int _i = 0; _i < 2; ++_i) \
;         __builtin_amdgcn_global_load_lds((const unsigned*)((const char*)(gbase) + (voff)[_i]), (PG8_LAS unsigned*)(lds + (bufoff) + ldsw + _i * 8192), 16, 0, 0); } while (0)
; #define PG8_LDA(dst, b, h) do { _Pragma("unroll") for (int m = 0; m < 4; ++m) _Pragma("unroll") for (int k = 0; k < 2; ++k) dst[m][k] = *(const PG8_LAS bf16x8*)(lds + PG8_SA(b, h) + aoff + m * 2048 + k * 1024); } while (0)
; #define PG8_LDB(dst, b, h) do { _Pragma("unroll") for (int n = 0; n < 2; ++n) _Pragma("unroll") for (int k = 0; k < 2; ++k) dst[n][k] = *(const PG8_LAS bf16x8*)(lds + PG8_SB(b, h) + boff + n * 2048 + k * 1024); } while (0)
; #define PG8_MMA(ai, bj, At, Bt) do { __builtin_amdgcn_s_setprio(1); _Pragma("unroll") for (int m = 0; m < 4; ++m) _Pragma("unroll") for (int n = 0; n < 2; ++n) _Pragma("unroll") for (int k = 0; k < 2; ++k) \
;         acc[ai][bj][m][n] = __builtin_amdgcn_mfma_f32_16x16x32_bf16(Bt[n][k], At[m][k], acc[ai][bj][m][n], 0, 0, 0); __builtin_amdgcn_s_setprio(0); } while (0)
; #define PG8_WAIT_V(n) asm volatile("s_waitcnt vmcnt(" #n ")" ::: "memory")
; #define PG8_WAIT_L(n) asm volatile("s_waitcnt lgkmcnt(" #n ")" ::: "memory")
; #define PG8_BAR __builtin_amdgcn_s_barrier()
; #define PG8_SCHED __builtin_amdgcn_sched_barrier(0)
; template <class Epi, class Sched, bool ALIGN_EPI = false, bool SP2 = false>
; __device__ __forceinline__ void gemm_phase(PG8_LAS unsigned char* lds, const Gemm g, const Sched& S, const Epi& E) {
;     ...
;             PG8_WAIT_V(8); PG8_WAIT_L(0); PG8_BAR; PG8_MMA(1, 0, At, B0); PG8_MMA(1, 1, At, B1); PG8_BAR; PG8_SCHED;
;             PG8_LDB(B0, 1, 0); PG8_LDB(B1, 1, 1); PG8_SCHED; PG8_LDA(At, 1, 0); PG8_STAGE(PG8_SA(0, 1), a2 + hstep, voffA);
;             PG8_WAIT_V(8); PG8_WAIT_L(0); PG8_BAR; PG8_MMA(0, 0, At, B0); PG8_MMA(0, 1, At, B1); PG8_BAR; PG8_SCHED;
	v_mfma_f32_16x16x32_bf16 v[92:95], v[146:149], v[188:191], v[92:95]
	v_mfma_f32_16x16x32_bf16 v[88:91], v[160:163], v[188:191], v[88:91]
	v_mfma_f32_16x16x32_bf16 v[84:87], v[146:149], v[196:199], v[84:87]
	v_mfma_f32_16x16x32_bf16 v[80:83], v[160:163], v[196:199], v[80:83]
	v_mfma_f32_16x16x32_bf16 v[76:79], v[146:149], v[204:207], v[76:79]
	v_mfma_f32_16x16x32_bf16 v[72:75], v[160:163], v[204:207], v[72:75]
	v_mfma_f32_16x16x32_bf16 v[68:71], v[146:149], v[212:215], v[68:71]
	v_mfma_f32_16x16x32_bf16 v[64:67], v[160:163], v[212:215], v[64:67]
	v_mfma_f32_16x16x32_bf16 v[92:95], v[150:153], v[192:195], v[92:95]
	v_mfma_f32_16x16x32_bf16 v[88:91], v[164:167], v[192:195], v[88:91]
	v_mfma_f32_16x16x32_bf16 v[84:87], v[150:153], v[200:203], v[84:87]
	v_mfma_f32_16x16x32_bf16 v[80:83], v[164:167], v[200:203], v[80:83]
	v_mfma_f32_16x16x32_bf16 v[76:79], v[150:153], v[208:211], v[76:79]
	v_mfma_f32_16x16x32_bf16 v[72:75], v[164:167], v[208:211], v[72:75]
	v_mfma_f32_16x16x32_bf16 v[68:71], v[150:153], v[216:219], v[68:71]
	v_mfma_f32_16x16x32_bf16 v[64:67], v[164:167], v[216:219], v[64:67]
	s_setprio 0
	s_setprio 1
	v_mfma_f32_16x16x32_bf16 v[28:31], v[172:175], v[188:191], v[28:31]
	v_mfma_f32_16x16x32_bf16 v[24:27], v[180:183], v[188:191], v[24:27]
	v_mfma_f32_16x16x32_bf16 v[20:23], v[172:175], v[196:199], v[20:23]
	v_mfma_f32_16x16x32_bf16 v[16:19], v[180:183], v[196:199], v[16:19]
	v_mfma_f32_16x16x32_bf16 v[12:15], v[172:175], v[204:207], v[12:15]
	v_mfma_f32_16x16x32_bf16 v[8:11], v[180:183], v[204:207], v[8:11]
	v_mfma_f32_16x16x32_bf16 v[4:7], v[172:175], v[212:215], v[4:7]
	v_mfma_f32_16x16x32_bf16 v[0:3], v[180:183], v[212:215], v[0:3]
	v_mfma_f32_16x16x32_bf16 v[28:31], v[176:179], v[192:195], v[28:31]
	v_mfma_f32_16x16x32_bf16 v[24:27], v[184:187], v[192:195], v[24:27]
	v_mfma_f32_16x16x32_bf16 v[20:23], v[176:179], v[200:203], v[20:23]
	v_mfma_f32_16x16x32_bf16 v[16:19], v[184:187], v[200:203], v[16:19]
	v_mfma_f32_16x16x32_bf16 v[12:15], v[176:179], v[208:211], v[12:15]
	v_mfma_f32_16x16x32_bf16 v[8:11], v[184:187], v[208:211], v[8:11]
	v_mfma_f32_16x16x32_bf16 v[4:7], v[176:179], v[216:219], v[4:7]
	v_mfma_f32_16x16x32_bf16 v[0:3], v[184:187], v[216:219], v[0:3]
	s_barrier
	s_setprio 0
	s_add_i32 s58, 0, 0x18000
	v_add_u32_e32 v136, s58, v154
	s_add_i32 s59, 0, 0x1c000
	ds_read_b128 v[146:149], v136
	ds_read_b128 v[150:153], v136 offset:1024
	ds_read_b128 v[160:163], v136 offset:2048
	ds_read_b128 v[164:167], v136 offset:3072
	v_add_u32_e32 v136, s59, v154
	ds_read_b128 v[172:175], v136
	ds_read_b128 v[176:179], v136 offset:1024
	ds_read_b128 v[180:183], v136 offset:2048
	ds_read_b128 v[184:187], v136 offset:3072
	s_add_u32 s36, s48, 0x80000
	s_addc_u32 s37, s49, 0
	s_mov_b32 m0, s50
	v_lshl_add_u64 v[226:227], s[36:37], 0, v[128:129]
	ds_read_b128 v[188:191], v158 offset:32768
	ds_read_b128 v[192:195], v158 offset:33792
	ds_read_b128 v[196:199], v158 offset:34816
	ds_read_b128 v[200:203], v158 offset:35840
	ds_read_b128 v[204:207], v158 offset:36864
	ds_read_b128 v[208:211], v158 offset:37888
	ds_read_b128 v[212:215], v158 offset:38912
	ds_read_b128 v[216:219], v158 offset:39936
	global_load_lds_dwordx4 v[226:227], off
	v_lshl_add_u64 v[226:227], s[36:37], 0, v[132:133]
	s_mov_b32 m0, s51
	s_nop 0
	global_load_lds_dwordx4 v[226:227], off
	s_waitcnt vmcnt(8)
	s_waitcnt lgkmcnt(0)
	s_setprio 1
	s_barrier
	v_mfma_f32_16x16x32_bf16 v[124:127], v[146:149], v[188:191], v[124:127]
	v_mfma_f32_16x16x32_bf16 v[120:123], v[160:163], v[188:191], v[120:123]
	v_mfma_f32_16x16x32_bf16 v[116:119], v[146:149], v[196:199], v[116:119]
	v_mfma_f32_16x16x32_bf16 v[112:115], v[160:163], v[196:199], v[112:115]
	v_mfma_f32_16x16x32_bf16 v[108:111], v[146:149], v[204:207], v[108:111]
	v_mfma_f32_16x16x32_bf16 v[104:107], v[160:163], v[204:207], v[104:107]
	v_mfma_f32_16x16x32_bf16 v[100:103], v[146:149], v[212:215], v[100:103]
	v_mfma_f32_16x16x32_bf16 v[96:99], v[160:163], v[212:215], v[96:99]
	v_mfma_f32_16x16x32_bf16 v[124:127], v[150:153], v[192:195], v[124:127]
	v_mfma_f32_16x16x32_bf16 v[120:123], v[164:167], v[192:195], v[120:123]
	v_mfma_f32_16x16x32_bf16 v[116:119], v[150:153], v[200:203], v[116:119]
	v_mfma_f32_16x16x32_bf16 v[112:115], v[164:167], v[200:203], v[112:115]
	v_mfma_f32_16x16x32_bf16 v[108:111], v[150:153], v[208:211], v[108:111]
	v_mfma_f32_16x16x32_bf16 v[104:107], v[164:167], v[208:211], v[104:107]
	v_mfma_f32_16x16x32_bf16 v[100:103], v[150:153], v[216:219], v[100:103]
	v_mfma_f32_16x16x32_bf16 v[96:99], v[164:167], v[216:219], v[96:99]
	s_setprio 0
	s_setprio 1
	v_mfma_f32_16x16x32_bf16 v[60:63], v[172:175], v[188:191], v[60:63]
	v_mfma_f32_16x16x32_bf16 v[56:59], v[180:183], v[188:191], v[56:59]
	v_mfma_f32_16x16x32_bf16 v[52:55], v[172:175], v[196:199], v[52:55]
	v_mfma_f32_16x16x32_bf16 v[48:51], v[180:183], v[196:199], v[48:51]
	v_mfma_f32_16x16x32_bf16 v[44:47], v[172:175], v[204:207], v[44:47]
	v_mfma_f32_16x16x32_bf16 v[40:43], v[180:183], v[204:207], v[40:43]
	v_mfma_f32_16x16x32_bf16 v[36:39], v[172:175], v[212:215], v[36:39]
	v_mfma_f32_16x16x32_bf16 v[32:35], v[180:183], v[212:215], v[32:35]
	v_mfma_f32_16x16x32_bf16 v[60:63], v[176:179], v[192:195], v[60:63]
	v_mfma_f32_16x16x32_bf16 v[56:59], v[184:187], v[192:195], v[56:59]
	v_mfma_f32_16x16x32_bf16 v[52:55], v[176:179], v[200:203], v[52:55]
	v_mfma_f32_16x16x32_bf16 v[48:51], v[184:187], v[200:203], v[48:51]
	v_mfma_f32_16x16x32_bf16 v[44:47], v[176:179], v[208:211], v[44:47]
	v_mfma_f32_16x16x32_bf16 v[40:43], v[184:187], v[208:211], v[40:43]
	v_mfma_f32_16x16x32_bf16 v[36:39], v[176:179], v[216:219], v[36:39]
	v_mfma_f32_16x16x32_bf16 v[32:35], v[184:187], v[216:219], v[32:35]
	s_barrier
; #define PG8_STAGE(bufoff, gbase, voff) do { _Pragma("unroll") for (int _i = 0; _i < 2; ++_i) \
;         __builtin_amdgcn_global_load_lds((const unsigned*)((const char*)(gbase) + (voff)[_i]), (PG8_LAS unsigned*)(lds + (bufoff) + ldsw + _i * 8192), 16, 0, 0); } while (0)
; #define PG8_LDA(dst, b, h) do { _Pragma("unroll") for (int m = 0; m < 4; ++m) _Pragma("unroll") for (int k = 0; k < 2; ++k) dst[m][k] = *(const PG8_LAS bf16x8*)(lds + PG8_SA(b, h) + aoff + m * 2048 + k * 1024); } while (0)
; #define PG8_MMA(ai, bj, At, Bt) do { __builtin_amdgcn_s_setprio(1); _Pragma("unroll") for (int m = 0; m < 4; ++m) _Pragma("unroll") for (int n = 0; n < 2; ++n) _Pragma("unroll") for (int k = 0; k < 2; ++k) \
;         acc[ai][bj][m][n] = __builtin_amdgcn_mfma_f32_16x16x32_bf16(Bt[n][k], At[m][k], acc[ai][bj][m][n], 0, 0, 0); __builtin_amdgcn_s_setprio(0); } while (0)
; #define PG8_WAIT_V(n) asm volatile("s_waitcnt vmcnt(" #n ")" ::: "memory")
; #define PG8_WAIT_L(n) asm volatile("s_waitcnt lgkmcnt(" #n ")" ::: "memory")
; #define PG8_BAR __builtin_amdgcn_s_barrier()
; #define PG8_SCHED __builtin_amdgcn_sched_barrier(0)
; template <class Epi, class Sched, bool ALIGN_EPI = false, bool SP2 = false>
; __device__ __forceinline__ void gemm_phase(PG8_LAS unsigned char* lds, const Gemm g, const Sched& S, const Epi& E) {
;     ...
;             PG8_LDA(At, 1, 1); PG8_STAGE(PG8_SB(1, 0), b3, voffB); PG8_STAGE(PG8_SB(1, 1), b3 + hstep, voffB); PG8_STAGE(PG8_SA(1, 0), a3, voffA);
;             PG8_WAIT_V(8); PG8_WAIT_L(0); PG8_BAR; PG8_MMA(1, 0, At, B0); PG8_MMA(1, 1, At, B1); PG8_BAR; PG8_SCHED;
;     ...
;         }
;         if constexpr (ALIGN_EPI) { if (wr == 0) PG8_BAR; }
	s_setprio 0
	s_add_i32 s36, s58, s19
	v_lshl_add_u64 v[168:169], v[168:169], 0, s[14:15]
	s_mov_b32 m0, s36
	ds_read_b128 v[188:191], v158 offset:49152
	ds_read_b128 v[192:195], v158 offset:50176
	ds_read_b128 v[196:199], v158 offset:51200
	ds_read_b128 v[200:203], v158 offset:52224
	ds_read_b128 v[204:207], v158 offset:53248
	ds_read_b128 v[208:211], v158 offset:54272
	ds_read_b128 v[212:215], v158 offset:55296
	ds_read_b128 v[216:219], v158 offset:56320
	global_load_lds_dwordx4 v[168:169], off
	s_add_i32 m0, s36, 0x2000
	s_add_u32 s34, s34, 0x80080
	v_lshl_add_u64 v[168:169], v[220:221], 0, s[14:15]
	s_addc_u32 s35, s35, 0
	s_add_i32 s36, s59, s19
	global_load_lds_dwordx4 v[168:169], off
	v_lshl_add_u64 v[168:169], s[34:35], 0, v[130:131]
	s_mov_b32 m0, s36
	s_nop 0
	global_load_lds_dwordx4 v[168:169], off
	v_lshl_add_u64 v[168:169], s[34:35], 0, v[134:135]
	s_add_i32 m0, s36, 0x2000
	s_nop 0
	global_load_lds_dwordx4 v[168:169], off
	v_lshl_add_u64 v[168:169], v[222:223], 0, s[14:15]
	s_mov_b32 m0, s53
	s_nop 0
	global_load_lds_dwordx4 v[168:169], off
	v_lshl_add_u64 v[168:169], v[224:225], 0, s[14:15]
	s_mov_b32 m0, s54
	s_nop 0
	global_load_lds_dwordx4 v[168:169], off
	s_waitcnt vmcnt(8)
	s_waitcnt lgkmcnt(0)
	s_setprio 1
	s_barrier
	v_mfma_f32_16x16x32_bf16 v[92:95], v[146:149], v[188:191], v[92:95]
	v_mfma_f32_16x16x32_bf16 v[88:91], v[160:163], v[188:191], v[88:91]
	v_mfma_f32_16x16x32_bf16 v[84:87], v[146:149], v[196:199], v[84:87]
	v_mfma_f32_16x16x32_bf16 v[80:83], v[160:163], v[196:199], v[80:83]
	v_mfma_f32_16x16x32_bf16 v[76:79], v[146:149], v[204:207], v[76:79]
	v_mfma_f32_16x16x32_bf16 v[72:75], v[160:163], v[204:207], v[72:75]
	v_mfma_f32_16x16x32_bf16 v[68:71], v[146:149], v[212:215], v[68:71]
	v_mfma_f32_16x16x32_bf16 v[64:67], v[160:163], v[212:215], v[64:67]
	v_mfma_f32_16x16x32_bf16 v[92:95], v[150:153], v[192:195], v[92:95]
	v_mfma_f32_16x16x32_bf16 v[88:91], v[164:167], v[192:195], v[88:91]
	v_mfma_f32_16x16x32_bf16 v[84:87], v[150:153], v[200:203], v[84:87]
	v_mfma_f32_16x16x32_bf16 v[80:83], v[164:167], v[200:203], v[80:83]
	v_mfma_f32_16x16x32_bf16 v[76:79], v[150:153], v[208:211], v[76:79]
	v_mfma_f32_16x16x32_bf16 v[72:75], v[164:167], v[208:211], v[72:75]
	v_mfma_f32_16x16x32_bf16 v[68:71], v[150:153], v[216:219], v[68:71]
	v_mfma_f32_16x16x32_bf16 v[64:67], v[164:167], v[216:219], v[64:67]
	s_setprio 0
	s_setprio 1
	v_mfma_f32_16x16x32_bf16 v[28:31], v[172:175], v[188:191], v[28:31]
	v_mfma_f32_16x16x32_bf16 v[24:27], v[180:183], v[188:191], v[24:27]
	v_mfma_f32_16x16x32_bf16 v[20:23], v[172:175], v[196:199], v[20:23]
	v_mfma_f32_16x16x32_bf16 v[16:19], v[180:183], v[196:199], v[16:19]
	v_mfma_f32_16x16x32_bf16 v[12:15], v[172:175], v[204:207], v[12:15]
	v_mfma_f32_16x16x32_bf16 v[8:11], v[180:183], v[204:207], v[8:11]
	v_mfma_f32_16x16x32_bf16 v[4:7], v[172:175], v[212:215], v[4:7]
	v_mfma_f32_16x16x32_bf16 v[0:3], v[180:183], v[212:215], v[0:3]
	v_mfma_f32_16x16x32_bf16 v[28:31], v[176:179], v[192:195], v[28:31]
	v_mfma_f32_16x16x32_bf16 v[24:27], v[184:187], v[192:195], v[24:27]
	v_mfma_f32_16x16x32_bf16 v[20:23], v[176:179], v[200:203], v[20:23]
	v_mfma_f32_16x16x32_bf16 v[16:19], v[184:187], v[200:203], v[16:19]
	v_mfma_f32_16x16x32_bf16 v[12:15], v[176:179], v[208:211], v[12:15]
	v_mfma_f32_16x16x32_bf16 v[8:11], v[184:187], v[208:211], v[8:11]
	v_mfma_f32_16x16x32_bf16 v[4:7], v[176:179], v[216:219], v[4:7]
	v_mfma_f32_16x16x32_bf16 v[0:3], v[184:187], v[216:219], v[0:3]
	s_barrier
	s_setprio 0
	s_add_i32 s81, s81, 2
	s_add_u32 s30, s30, 0x100
	s_addc_u32 s31, s31, 0
	s_add_u32 s79, s79, 0x100
	s_addc_u32 s80, s80, 0
	s_cmp_gt_u32 s81, 29
	s_cbranch_scc0 .LBB0_393
	s_and_b64 vcc, exec, s[16:17]
	s_cbranch_vccz .LBB0_396
	s_barrier

; #define PG8_STAGE(bufoff, gbase, voff) do { _Pragma("unroll") for (int _i = 0; _i < 2; ++_i) \
;         __builtin_amdgcn_global_load_lds((const unsigned*)((const char*)(gbase) + (voff)[_i]), (PG8_LAS unsigned*)(lds + (bufoff) + ldsw + _i * 8192), 16, 0, 0); } while (0)
; #define PG8_LDA(dst, b, h) do { _Pragma("unroll") for (int m = 0; m < 4; ++m) _Pragma("unroll") for (int k = 0; k < 2; ++k) dst[m][k] = *(const PG8_LAS bf16x8*)(lds + PG8_SA(b, h) + aoff + m * 2048 + k * 1024); } while (0)
; #define PG8_LDB(dst, b, h) do { _Pragma("unroll") for (int n = 0; n < 2; ++n) _Pragma("unroll") for (int k = 0; k < 2; ++k) dst[n][k] = *(const PG8_LAS bf16x8*)(lds + PG8_SB(b, h) + boff + n * 2048 + k * 1024); } while (0)
; #define PG8_MMA(ai, bj, At, Bt) do { __builtin_amdgcn_s_setprio(1); _Pragma("unroll") for (int m = 0; m < 4; ++m) _Pragma("unroll") for (int n = 0; n < 2; ++n) _Pragma("unroll") for (int k = 0; k < 2; ++k) \
;         acc[ai][bj][m][n] = __builtin_amdgcn_mfma_f32_16x16x32_bf16(Bt[n][k], At[m][k], acc[ai][bj][m][n], 0, 0, 0); __builtin_amdgcn_s_setprio(0); } while (0)
; #define PG8_WAIT_V(n) asm volatile("s_waitcnt vmcnt(" #n ")" ::: "memory")
; #define PG8_WAIT_L(n) asm volatile("s_waitcnt lgkmcnt(" #n ")" ::: "memory")
; #define PG8_BAR __builtin_amdgcn_s_barrier()
; #define PG8_SCHED __builtin_amdgcn_sched_barrier(0)
; template <class Epi, class Sched, bool ALIGN_EPI = false, bool SP2 = false>
; __device__ __forceinline__ void gemm_phase(PG8_LAS unsigned char* lds, const Gemm g, const Sched& S, const Epi& E) {
;     ...
;             PG8_LDB(B0, 0, 0); PG8_LDB(B1, 0, 1); PG8_SCHED; PG8_LDA(At, 0, 0); PG8_STAGE(PG8_SA(1, 1), a1 + hstep, voffA);
;             PG8_WAIT_V(8); PG8_WAIT_L(0); PG8_BAR; PG8_MMA(0, 0, At, B0); PG8_MMA(0, 1, At, B1); PG8_BAR; PG8_SCHED;
;             PG8_LDA(At, 0, 1); PG8_STAGE(PG8_SB(0, 0), b2, voffB); PG8_STAGE(PG8_SB(0, 1), b2 + hstep, voffB); PG8_STAGE(PG8_SA(0, 0), a2, voffA);
;             PG8_WAIT_V(8); PG8_WAIT_L(0); PG8_BAR; PG8_MMA(1, 0, At, B0); PG8_MMA(1, 1, At, B1); PG8_BAR; PG8_SCHED;
.LBB0_523:
	ds_read_b128 v[154:157], v151
	ds_read_b128 v[158:161], v151 offset:1024
	ds_read_b128 v[162:165], v151 offset:2048
	ds_read_b128 v[166:169], v151 offset:3072
	ds_read_b128 v[174:177], v152
	ds_read_b128 v[178:181], v152 offset:1024
	ds_read_b128 v[182:185], v152 offset:2048
	ds_read_b128 v[186:189], v152 offset:3072
	s_add_u32 s30, s28, 0xfff80080
	s_addc_u32 s31, s29, -1
	s_cmp_eq_u32 s80, 28
	s_cselect_b32 s35, s21, s31
	s_cselect_b32 s34, s76, s30
	s_cselect_b32 s31, s19, s79
	s_cselect_b32 s30, s77, s78
	v_lshl_add_u64 v[148:149], s[28:29], 0, v[140:141]
	s_add_i32 m0, s27, 0xc000
	ds_read_b128 v[190:193], v153
	ds_read_b128 v[194:197], v153 offset:1024
	ds_read_b128 v[198:201], v153 offset:2048
	ds_read_b128 v[202:205], v153 offset:3072
	ds_read_b128 v[206:209], v153 offset:4096
	ds_read_b128 v[210:213], v153 offset:5120
	ds_read_b128 v[214:217], v153 offset:6144
	ds_read_b128 v[218:221], v153 offset:7168
	global_load_lds_dwordx4 v[148:149], off
	v_lshl_add_u64 v[148:149], s[28:29], 0, v[142:143]
	s_add_i32 m0, s27, 0xe000
	s_nop 0
	global_load_lds_dwordx4 v[148:149], off
	s_waitcnt vmcnt(8)
	s_waitcnt lgkmcnt(0)
	s_setprio 1
	s_barrier
	v_mfma_f32_16x16x32_bf16 v[124:127], v[154:157], v[190:193], v[124:127]
	v_mfma_f32_16x16x32_bf16 v[120:123], v[162:165], v[190:193], v[120:123]
	v_mfma_f32_16x16x32_bf16 v[108:111], v[154:157], v[198:201], v[108:111]
	v_mfma_f32_16x16x32_bf16 v[104:107], v[162:165], v[198:201], v[104:107]
	v_mfma_f32_16x16x32_bf16 v[92:95], v[154:157], v[206:209], v[92:95]
	v_mfma_f32_16x16x32_bf16 v[88:91], v[162:165], v[206:209], v[88:91]
	v_mfma_f32_16x16x32_bf16 v[76:79], v[154:157], v[214:217], v[76:79]
	v_mfma_f32_16x16x32_bf16 v[72:75], v[162:165], v[214:217], v[72:75]
	v_mfma_f32_16x16x32_bf16 v[124:127], v[158:161], v[194:197], v[124:127]
	v_mfma_f32_16x16x32_bf16 v[120:123], v[166:169], v[194:197], v[120:123]
	v_mfma_f32_16x16x32_bf16 v[108:111], v[158:161], v[202:205], v[108:111]
	v_mfma_f32_16x16x32_bf16 v[104:107], v[166:169], v[202:205], v[104:107]
	v_mfma_f32_16x16x32_bf16 v[92:95], v[158:161], v[210:213], v[92:95]
	v_mfma_f32_16x16x32_bf16 v[88:91], v[166:169], v[210:213], v[88:91]
	v_mfma_f32_16x16x32_bf16 v[76:79], v[158:161], v[218:221], v[76:79]
	v_mfma_f32_16x16x32_bf16 v[72:75], v[166:169], v[218:221], v[72:75]
	s_setprio 0
	s_setprio 1
	v_mfma_f32_16x16x32_bf16 v[116:119], v[174:177], v[190:193], v[116:119]
	v_mfma_f32_16x16x32_bf16 v[112:115], v[182:185], v[190:193], v[112:115]
	v_mfma_f32_16x16x32_bf16 v[100:103], v[174:177], v[198:201], v[100:103]
	v_mfma_f32_16x16x32_bf16 v[96:99], v[182:185], v[198:201], v[96:99]
	v_mfma_f32_16x16x32_bf16 v[84:87], v[174:177], v[206:209], v[84:87]
	v_mfma_f32_16x16x32_bf16 v[80:83], v[182:185], v[206:209], v[80:83]
	v_mfma_f32_16x16x32_bf16 v[68:71], v[174:177], v[214:217], v[68:71]
	v_mfma_f32_16x16x32_bf16 v[64:67], v[182:185], v[214:217], v[64:67]
	v_mfma_f32_16x16x32_bf16 v[116:119], v[178:181], v[194:197], v[116:119]
	v_mfma_f32_16x16x32_bf16 v[112:115], v[186:189], v[194:197], v[112:115]
	v_mfma_f32_16x16x32_bf16 v[100:103], v[178:181], v[202:205], v[100:103]
	v_mfma_f32_16x16x32_bf16 v[96:99], v[186:189], v[202:205], v[96:99]
	v_mfma_f32_16x16x32_bf16 v[84:87], v[178:181], v[210:213], v[84:87]
	v_mfma_f32_16x16x32_bf16 v[80:83], v[186:189], v[210:213], v[80:83]
	v_mfma_f32_16x16x32_bf16 v[68:71], v[178:181], v[218:221], v[68:71]
	v_mfma_f32_16x16x32_bf16 v[64:67], v[186:189], v[218:221], v[64:67]
	s_barrier
	s_setprio 0
	s_add_i32 s36, s72, s3
	v_lshl_add_u64 v[148:149], s[30:31], 0, v[132:133]
	s_mov_b32 m0, s36
	ds_read_b128 v[190:193], v153 offset:16384
	ds_read_b128 v[194:197], v153 offset:17408
	ds_read_b128 v[198:201], v153 offset:18432
	ds_read_b128 v[202:205], v153 offset:19456
	ds_read_b128 v[206:209], v153 offset:20480
	ds_read_b128 v[210:213], v153 offset:21504
	ds_read_b128 v[214:217], v153 offset:22528
	ds_read_b128 v[218:221], v153 offset:23552
	global_load_lds_dwordx4 v[148:149], off
	s_add_i32 m0, s36, 0x2000
	s_add_u32 s36, s30, 0x80000
	v_lshl_add_u64 v[222:223], s[30:31], 0, v[128:129]
	s_addc_u32 s37, s31, 0
	s_add_i32 s58, s73, s3
	global_load_lds_dwordx4 v[222:223], off
	v_lshl_add_u64 v[224:225], s[36:37], 0, v[132:133]
	s_mov_b32 m0, s58
	v_lshl_add_u64 v[226:227], s[34:35], 0, v[130:131]
	global_load_lds_dwordx4 v[224:225], off
	v_lshl_add_u64 v[224:225], s[36:37], 0, v[128:129]
	s_add_i32 m0, s58, 0x2000
	s_nop 0
	global_load_lds_dwordx4 v[224:225], off
	v_lshl_add_u64 v[224:225], s[34:35], 0, v[134:135]
	s_mov_b32 m0, s27
	s_nop 0
	global_load_lds_dwordx4 v[224:225], off
	s_mov_b32 m0, s49
	s_nop 0
	global_load_lds_dwordx4 v[226:227], off
	s_waitcnt vmcnt(8)
	s_waitcnt lgkmcnt(0)
	s_setprio 1
	s_barrier
; #define PG8_STAGE(bufoff, gbase, voff) do { _Pragma("unroll") for (int _i = 0; _i < 2; ++_i) \
;         __builtin_amdgcn_global_load_lds((const unsigned*)((const char*)(gbase) + (voff)[_i]), (PG8_LAS unsigned*)(lds + (bufoff) + ldsw + _i * 8192), 16, 0, 0); } while (0)
; #define PG8_LDA(dst, b, h) do { _Pragma("unroll") for (int m = 0; m < 4; ++m) _Pragma("unroll") for (int k = 0; k < 2; ++k) dst[m][k] = *(const PG8_LAS bf16x8*)(lds + PG8_SA(b, h) + aoff + m * 2048 + k * 1024); } while (0)
; #define PG8_LDB(dst, b, h) do { _Pragma("unroll") for (int n = 0; n < 2; ++n) _Pragma("unroll") for (int k = 0; k < 2; ++k) dst[n][k] = *(const PG8_LAS bf16x8*)(lds + PG8_SB(b, h) + boff + n * 2048 + k * 1024); } while (0)
; #define PG8_MMA(ai, bj, At, Bt) do { __builtin_amdgcn_s_setprio(1); _Pragma("unroll") for (int m = 0; m < 4; ++m) _Pragma("unroll") for (int n = 0; n < 2; ++n) _Pragma("unroll") for (int k = 0; k < 2; ++k) \
;         acc[ai][bj][m][n] = __builtin_amdgcn_mfma_f32_16x16x32_bf16(Bt[n][k], At[m][k], acc[ai][bj][m][n], 0, 0, 0); __builtin_amdgcn_s_setprio(0); } while (0)
; #define PG8_WAIT_V(n) asm volatile("s_waitcnt vmcnt(" #n ")" ::: "memory")
; #define PG8_WAIT_L(n) asm volatile("s_waitcnt lgkmcnt(" #n ")" ::: "memory")
; #define PG8_BAR __builtin_amdgcn_s_barrier()
; #define PG8_SCHED __builtin_amdgcn_sched_barrier(0)
; template <class Epi, class Sched, bool ALIGN_EPI = false, bool SP2 = false>
; __device__ __forceinline__ void gemm_phase(PG8_LAS unsigned char* lds, const Gemm g, const Sched& S, const Epi& E) {
;     ...
;             PG8_WAIT_V(8); PG8_WAIT_L(0); PG8_BAR; PG8_MMA(1, 0, At, B0); PG8_MMA(1, 1, At, B1); PG8_BAR; PG8_SCHED;
;             PG8_LDB(B0, 1, 0); PG8_LDB(B1, 1, 1); PG8_SCHED; PG8_LDA(At, 1, 0); PG8_STAGE(PG8_SA(0, 1), a2 + hstep, voffA);
;             PG8_WAIT_V(8); PG8_WAIT_L(0); PG8_BAR; PG8_MMA(0, 0, At, B0); PG8_MMA(0, 1, At, B1); PG8_BAR; PG8_SCHED;
	v_mfma_f32_16x16x32_bf16 v[60:63], v[154:157], v[190:193], v[60:63]
	v_mfma_f32_16x16x32_bf16 v[56:59], v[162:165], v[190:193], v[56:59]
	v_mfma_f32_16x16x32_bf16 v[44:47], v[154:157], v[198:201], v[44:47]
	v_mfma_f32_16x16x32_bf16 v[40:43], v[162:165], v[198:201], v[40:43]
	v_mfma_f32_16x16x32_bf16 v[28:31], v[154:157], v[206:209], v[28:31]
	v_mfma_f32_16x16x32_bf16 v[24:27], v[162:165], v[206:209], v[24:27]
	v_mfma_f32_16x16x32_bf16 v[12:15], v[154:157], v[214:217], v[12:15]
	v_mfma_f32_16x16x32_bf16 v[8:11], v[162:165], v[214:217], v[8:11]
	v_mfma_f32_16x16x32_bf16 v[60:63], v[158:161], v[194:197], v[60:63]
	v_mfma_f32_16x16x32_bf16 v[56:59], v[166:169], v[194:197], v[56:59]
	v_mfma_f32_16x16x32_bf16 v[44:47], v[158:161], v[202:205], v[44:47]
	v_mfma_f32_16x16x32_bf16 v[40:43], v[166:169], v[202:205], v[40:43]
	v_mfma_f32_16x16x32_bf16 v[28:31], v[158:161], v[210:213], v[28:31]
	v_mfma_f32_16x16x32_bf16 v[24:27], v[166:169], v[210:213], v[24:27]
	v_mfma_f32_16x16x32_bf16 v[12:15], v[158:161], v[218:221], v[12:15]
	v_mfma_f32_16x16x32_bf16 v[8:11], v[166:169], v[218:221], v[8:11]
	s_setprio 0
	s_setprio 1
	v_mfma_f32_16x16x32_bf16 v[52:55], v[174:177], v[190:193], v[52:55]
	v_mfma_f32_16x16x32_bf16 v[48:51], v[182:185], v[190:193], v[48:51]
	v_mfma_f32_16x16x32_bf16 v[36:39], v[174:177], v[198:201], v[36:39]
	v_mfma_f32_16x16x32_bf16 v[32:35], v[182:185], v[198:201], v[32:35]
	v_mfma_f32_16x16x32_bf16 v[20:23], v[174:177], v[206:209], v[20:23]
	v_mfma_f32_16x16x32_bf16 v[16:19], v[182:185], v[206:209], v[16:19]
	v_mfma_f32_16x16x32_bf16 v[4:7], v[174:177], v[214:217], v[4:7]
	v_mfma_f32_16x16x32_bf16 v[0:3], v[182:185], v[214:217], v[0:3]
	v_mfma_f32_16x16x32_bf16 v[52:55], v[178:181], v[194:197], v[52:55]
	v_mfma_f32_16x16x32_bf16 v[48:51], v[186:189], v[194:197], v[48:51]
	v_mfma_f32_16x16x32_bf16 v[36:39], v[178:181], v[202:205], v[36:39]
	v_mfma_f32_16x16x32_bf16 v[32:35], v[186:189], v[202:205], v[32:35]
	v_mfma_f32_16x16x32_bf16 v[20:23], v[178:181], v[210:213], v[20:23]
	v_mfma_f32_16x16x32_bf16 v[16:19], v[186:189], v[210:213], v[16:19]
	v_mfma_f32_16x16x32_bf16 v[4:7], v[178:181], v[218:221], v[4:7]
	v_mfma_f32_16x16x32_bf16 v[0:3], v[186:189], v[218:221], v[0:3]
	s_barrier
	s_setprio 0
	s_add_i32 s36, 0, 0x18000
	s_add_i32 s37, 0, 0x1c000
	v_add_u32_e32 v166, s36, v139
	v_add_u32_e32 v171, s37, v139
	ds_read_b128 v[154:157], v166
	ds_read_b128 v[158:161], v166 offset:1024
	ds_read_b128 v[162:165], v166 offset:2048
	ds_read_b128 v[166:169], v166 offset:3072
	ds_read_b128 v[174:177], v171
	ds_read_b128 v[178:181], v171 offset:1024
	ds_read_b128 v[182:185], v171 offset:2048
	ds_read_b128 v[186:189], v171 offset:3072
	s_add_u32 s34, s34, 0x80000
	s_addc_u32 s35, s35, 0
	s_mov_b32 m0, s50
	v_lshl_add_u64 v[228:229], s[34:35], 0, v[134:135]
	ds_read_b128 v[190:193], v153 offset:32768
	ds_read_b128 v[194:197], v153 offset:33792
	ds_read_b128 v[198:201], v153 offset:34816
	ds_read_b128 v[202:205], v153 offset:35840
	ds_read_b128 v[206:209], v153 offset:36864
	ds_read_b128 v[210:213], v153 offset:37888
	ds_read_b128 v[214:217], v153 offset:38912
	ds_read_b128 v[218:221], v153 offset:39936
	global_load_lds_dwordx4 v[228:229], off
	v_lshl_add_u64 v[228:229], s[34:35], 0, v[130:131]
	s_mov_b32 m0, s51
	s_nop 0
	global_load_lds_dwordx4 v[228:229], off
	s_waitcnt vmcnt(8)
	s_waitcnt lgkmcnt(0)
	s_setprio 1
	s_barrier
	v_mfma_f32_16x16x32_bf16 v[124:127], v[154:157], v[190:193], v[124:127]
	v_mfma_f32_16x16x32_bf16 v[120:123], v[162:165], v[190:193], v[120:123]
	v_mfma_f32_16x16x32_bf16 v[108:111], v[154:157], v[198:201], v[108:111]
	v_mfma_f32_16x16x32_bf16 v[104:107], v[162:165], v[198:201], v[104:107]
	v_mfma_f32_16x16x32_bf16 v[92:95], v[154:157], v[206:209], v[92:95]
	v_mfma_f32_16x16x32_bf16 v[88:91], v[162:165], v[206:209], v[88:91]
	v_mfma_f32_16x16x32_bf16 v[76:79], v[154:157], v[214:217], v[76:79]
	v_mfma_f32_16x16x32_bf16 v[72:75], v[162:165], v[214:217], v[72:75]
	v_mfma_f32_16x16x32_bf16 v[124:127], v[158:161], v[194:197], v[124:127]
	v_mfma_f32_16x16x32_bf16 v[120:123], v[166:169], v[194:197], v[120:123]
	v_mfma_f32_16x16x32_bf16 v[108:111], v[158:161], v[202:205], v[108:111]
	v_mfma_f32_16x16x32_bf16 v[104:107], v[166:169], v[202:205], v[104:107]
	v_mfma_f32_16x16x32_bf16 v[92:95], v[158:161], v[210:213], v[92:95]
	v_mfma_f32_16x16x32_bf16 v[88:91], v[166:169], v[210:213], v[88:91]
	v_mfma_f32_16x16x32_bf16 v[76:79], v[158:161], v[218:221], v[76:79]
	v_mfma_f32_16x16x32_bf16 v[72:75], v[166:169], v[218:221], v[72:75]
	s_setprio 0
	s_setprio 1
	v_mfma_f32_16x16x32_bf16 v[116:119], v[174:177], v[190:193], v[116:119]
	v_mfma_f32_16x16x32_bf16 v[112:115], v[182:185], v[190:193], v[112:115]
	v_mfma_f32_16x16x32_bf16 v[100:103], v[174:177], v[198:201], v[100:103]
	v_mfma_f32_16x16x32_bf16 v[96:99], v[182:185], v[198:201], v[96:99]
	v_mfma_f32_16x16x32_bf16 v[84:87], v[174:177], v[206:209], v[84:87]
	v_mfma_f32_16x16x32_bf16 v[80:83], v[182:185], v[206:209], v[80:83]
	v_mfma_f32_16x16x32_bf16 v[68:71], v[174:177], v[214:217], v[68:71]
	v_mfma_f32_16x16x32_bf16 v[64:67], v[182:185], v[214:217], v[64:67]
	v_mfma_f32_16x16x32_bf16 v[116:119], v[178:181], v[194:197], v[116:119]
	v_mfma_f32_16x16x32_bf16 v[112:115], v[186:189], v[194:197], v[112:115]
	v_mfma_f32_16x16x32_bf16 v[100:103], v[178:181], v[202:205], v[100:103]
	v_mfma_f32_16x16x32_bf16 v[96:99], v[186:189], v[202:205], v[96:99]
	v_mfma_f32_16x16x32_bf16 v[84:87], v[178:181], v[210:213], v[84:87]
	v_mfma_f32_16x16x32_bf16 v[80:83], v[186:189], v[210:213], v[80:83]
	v_mfma_f32_16x16x32_bf16 v[68:71], v[178:181], v[218:221], v[68:71]
	v_mfma_f32_16x16x32_bf16 v[64:67], v[186:189], v[218:221], v[64:67]
	s_barrier
; #define PG8_STAGE(bufoff, gbase, voff) do { _Pragma("unroll") for (int _i = 0; _i < 2; ++_i) \
;         __builtin_amdgcn_global_load_lds((const unsigned*)((const char*)(gbase) + (voff)[_i]), (PG8_LAS unsigned*)(lds + (bufoff) + ldsw + _i * 8192), 16, 0, 0); } while (0)
; #define PG8_LDA(dst, b, h) do { _Pragma("unroll") for (int m = 0; m < 4; ++m) _Pragma("unroll") for (int k = 0; k < 2; ++k) dst[m][k] = *(const PG8_LAS bf16x8*)(lds + PG8_SA(b, h) + aoff + m * 2048 + k * 1024); } while (0)
; #define PG8_MMA(ai, bj, At, Bt) do { __builtin_amdgcn_s_setprio(1); _Pragma("unroll") for (int m = 0; m < 4; ++m) _Pragma("unroll") for (int n = 0; n < 2; ++n) _Pragma("unroll") for (int k = 0; k < 2; ++k) \
;         acc[ai][bj][m][n] = __builtin_amdgcn_mfma_f32_16x16x32_bf16(Bt[n][k], At[m][k], acc[ai][bj][m][n], 0, 0, 0); __builtin_amdgcn_s_setprio(0); } while (0)
; #define PG8_WAIT_V(n) asm volatile("s_waitcnt vmcnt(" #n ")" ::: "memory")
; #define PG8_WAIT_L(n) asm volatile("s_waitcnt lgkmcnt(" #n ")" ::: "memory")
; #define PG8_BAR __builtin_amdgcn_s_barrier()
; #define PG8_SCHED __builtin_amdgcn_sched_barrier(0)
; template <class Epi, class Sched, bool ALIGN_EPI = false, bool SP2 = false>
; __device__ __forceinline__ void gemm_phase(PG8_LAS unsigned char* lds, const Gemm g, const Sched& S, const Epi& E) {
;     ...
;             PG8_LDA(At, 1, 1); PG8_STAGE(PG8_SB(1, 0), b3, voffB); PG8_STAGE(PG8_SB(1, 1), b3 + hstep, voffB); PG8_STAGE(PG8_SA(1, 0), a3, voffA);
;             PG8_WAIT_V(8); PG8_WAIT_L(0); PG8_BAR; PG8_MMA(1, 0, At, B0); PG8_MMA(1, 1, At, B1); PG8_BAR; PG8_SCHED;
;     ...
;         }
;         if constexpr (ALIGN_EPI) { if (wr == 0) PG8_BAR; }
	s_setprio 0
	s_add_i32 s34, s36, s3
	v_lshl_add_u64 v[148:149], v[148:149], 0, s[14:15]
	s_mov_b32 m0, s34
	ds_read_b128 v[190:193], v153 offset:49152
	ds_read_b128 v[194:197], v153 offset:50176
	ds_read_b128 v[198:201], v153 offset:51200
	ds_read_b128 v[202:205], v153 offset:52224
	ds_read_b128 v[206:209], v153 offset:53248
	ds_read_b128 v[210:213], v153 offset:54272
	ds_read_b128 v[214:217], v153 offset:55296
	ds_read_b128 v[218:221], v153 offset:56320
	global_load_lds_dwordx4 v[148:149], off
	s_add_i32 m0, s34, 0x2000
	s_add_u32 s30, s30, 0x80080
	v_lshl_add_u64 v[148:149], v[222:223], 0, s[14:15]
	s_addc_u32 s31, s31, 0
	s_add_i32 s34, s37, s3
	global_load_lds_dwordx4 v[148:149], off
	v_lshl_add_u64 v[148:149], s[30:31], 0, v[132:133]
	s_mov_b32 m0, s34
	s_nop 0
	global_load_lds_dwordx4 v[148:149], off
	v_lshl_add_u64 v[148:149], s[30:31], 0, v[128:129]
	s_add_i32 m0, s34, 0x2000
	s_nop 0
	global_load_lds_dwordx4 v[148:149], off
	v_lshl_add_u64 v[148:149], v[224:225], 0, s[14:15]
	s_mov_b32 m0, s53
	s_nop 0
	global_load_lds_dwordx4 v[148:149], off
	v_lshl_add_u64 v[148:149], v[226:227], 0, s[14:15]
	s_mov_b32 m0, s54
	s_nop 0
	global_load_lds_dwordx4 v[148:149], off
	s_waitcnt vmcnt(8)
	s_waitcnt lgkmcnt(0)
	s_setprio 1
	s_barrier
	v_mfma_f32_16x16x32_bf16 v[60:63], v[154:157], v[190:193], v[60:63]
	v_mfma_f32_16x16x32_bf16 v[56:59], v[162:165], v[190:193], v[56:59]
	v_mfma_f32_16x16x32_bf16 v[44:47], v[154:157], v[198:201], v[44:47]
	v_mfma_f32_16x16x32_bf16 v[40:43], v[162:165], v[198:201], v[40:43]
	v_mfma_f32_16x16x32_bf16 v[28:31], v[154:157], v[206:209], v[28:31]
	v_mfma_f32_16x16x32_bf16 v[24:27], v[162:165], v[206:209], v[24:27]
	v_mfma_f32_16x16x32_bf16 v[12:15], v[154:157], v[214:217], v[12:15]
	v_mfma_f32_16x16x32_bf16 v[8:11], v[162:165], v[214:217], v[8:11]
	v_mfma_f32_16x16x32_bf16 v[60:63], v[158:161], v[194:197], v[60:63]
	v_mfma_f32_16x16x32_bf16 v[56:59], v[166:169], v[194:197], v[56:59]
	v_mfma_f32_16x16x32_bf16 v[44:47], v[158:161], v[202:205], v[44:47]
	v_mfma_f32_16x16x32_bf16 v[40:43], v[166:169], v[202:205], v[40:43]
	v_mfma_f32_16x16x32_bf16 v[28:31], v[158:161], v[210:213], v[28:31]
	v_mfma_f32_16x16x32_bf16 v[24:27], v[166:169], v[210:213], v[24:27]
	v_mfma_f32_16x16x32_bf16 v[12:15], v[158:161], v[218:221], v[12:15]
	v_mfma_f32_16x16x32_bf16 v[8:11], v[166:169], v[218:221], v[8:11]
	s_setprio 0
	s_setprio 1
	v_mfma_f32_16x16x32_bf16 v[52:55], v[174:177], v[190:193], v[52:55]
	v_mfma_f32_16x16x32_bf16 v[48:51], v[182:185], v[190:193], v[48:51]
	v_mfma_f32_16x16x32_bf16 v[36:39], v[174:177], v[198:201], v[36:39]
	v_mfma_f32_16x16x32_bf16 v[32:35], v[182:185], v[198:201], v[32:35]
	v_mfma_f32_16x16x32_bf16 v[20:23], v[174:177], v[206:209], v[20:23]
	v_mfma_f32_16x16x32_bf16 v[16:19], v[182:185], v[206:209], v[16:19]
	v_mfma_f32_16x16x32_bf16 v[4:7], v[174:177], v[214:217], v[4:7]
	v_mfma_f32_16x16x32_bf16 v[0:3], v[182:185], v[214:217], v[0:3]
	v_mfma_f32_16x16x32_bf16 v[52:55], v[178:181], v[194:197], v[52:55]
	v_mfma_f32_16x16x32_bf16 v[48:51], v[186:189], v[194:197], v[48:51]
	v_mfma_f32_16x16x32_bf16 v[36:39], v[178:181], v[202:205], v[36:39]
	v_mfma_f32_16x16x32_bf16 v[32:35], v[186:189], v[202:205], v[32:35]
	v_mfma_f32_16x16x32_bf16 v[20:23], v[178:181], v[210:213], v[20:23]
	v_mfma_f32_16x16x32_bf16 v[16:19], v[186:189], v[210:213], v[16:19]
	v_mfma_f32_16x16x32_bf16 v[4:7], v[178:181], v[218:221], v[4:7]
	v_mfma_f32_16x16x32_bf16 v[0:3], v[186:189], v[218:221], v[0:3]
	s_barrier
	s_setprio 0
	s_add_i32 s80, s80, 2
	s_add_u32 s28, s28, 0x100
	s_addc_u32 s29, s29, 0
	s_add_u32 s78, s78, 0x100
	s_addc_u32 s79, s79, 0
	s_cmp_gt_u32 s80, 29
	s_cbranch_scc0 .LBB0_523
	s_and_b64 vcc, exec, s[16:17]
	s_cbranch_vccz .LBB0_526
	s_barrier

; #define PG8_STAGE(bufoff, gbase, voff) do { _Pragma("unroll") for (int _i = 0; _i < 2; ++_i) \
;         __builtin_amdgcn_global_load_lds((const unsigned*)((const char*)(gbase) + (voff)[_i]), (PG8_LAS unsigned*)(lds + (bufoff) + ldsw + _i * 8192), 16, 0, 0); } while (0)
; #define PG8_LDA(dst, b, h) do { _Pragma("unroll") for (int m = 0; m < 4; ++m) _Pragma("unroll") for (int k = 0; k < 2; ++k) dst[m][k] = *(const PG8_LAS bf16x8*)(lds + PG8_SA(b, h) + aoff + m * 2048 + k * 1024); } while (0)
; #define PG8_LDB(dst, b, h) do { _Pragma("unroll") for (int n = 0; n < 2; ++n) _Pragma("unroll") for (int k = 0; k < 2; ++k) dst[n][k] = *(const PG8_LAS bf16x8*)(lds + PG8_SB(b, h) + boff + n * 2048 + k * 1024); } while (0)
; #define PG8_MMA(ai, bj, At, Bt) do { __builtin_amdgcn_s_setprio(1); _Pragma("unroll") for (int m = 0; m < 4; ++m) _Pragma("unroll") for (int n = 0; n < 2; ++n) _Pragma("unroll") for (int k = 0; k < 2; ++k) \
;         acc[ai][bj][m][n] = __builtin_amdgcn_mfma_f32_16x16x32_bf16(Bt[n][k], At[m][k], acc[ai][bj][m][n], 0, 0, 0); __builtin_amdgcn_s_setprio(0); } while (0)
; #define PG8_WAIT_V(n) asm volatile("s_waitcnt vmcnt(" #n ")" ::: "memory")
; #define PG8_WAIT_L(n) asm volatile("s_waitcnt lgkmcnt(" #n ")" ::: "memory")
; #define PG8_BAR __builtin_amdgcn_s_barrier()
; #define PG8_SCHED __builtin_amdgcn_sched_barrier(0)
; template <class Epi, class Sched, bool ALIGN_EPI = false, bool SP2 = false>
; __device__ __forceinline__ void gemm_phase(PG8_LAS unsigned char* lds, const Gemm g, const Sched& S, const Epi& E) {
;     ...
;             PG8_LDB(B0, 0, 0); PG8_LDB(B1, 0, 1); PG8_SCHED; PG8_LDA(At, 0, 0); PG8_STAGE(PG8_SA(1, 1), a1 + hstep, voffA);
;             PG8_WAIT_V(8); PG8_WAIT_L(0); PG8_BAR; PG8_MMA(0, 0, At, B0); PG8_MMA(0, 1, At, B1); PG8_BAR; PG8_SCHED;
;             PG8_LDA(At, 0, 1); PG8_STAGE(PG8_SB(0, 0), b2, voffB); PG8_STAGE(PG8_SB(0, 1), b2 + hstep, voffB); PG8_STAGE(PG8_SA(0, 0), a2, voffA);
;             PG8_WAIT_V(8); PG8_WAIT_L(0); PG8_BAR; PG8_MMA(1, 0, At, B0); PG8_MMA(1, 1, At, B1); PG8_BAR; PG8_SCHED;
.LBB0_606:
	ds_read_b128 v[150:153], v158
	ds_read_b128 v[154:157], v158 offset:1024
	ds_read_b128 v[162:165], v158 offset:2048
	ds_read_b128 v[166:169], v158 offset:3072
	ds_read_b128 v[174:177], v159
	ds_read_b128 v[178:181], v159 offset:1024
	ds_read_b128 v[182:185], v159 offset:2048
	ds_read_b128 v[186:189], v159 offset:3072
	s_add_u32 s26, s24, 0xffea0080
	s_addc_u32 s27, s25, -1
	s_cmpk_eq_i32 s73, 0x54
	s_cselect_b32 s29, s7, s27
	s_cselect_b32 s28, s6, s26
	s_cselect_b32 s27, s23, s72
	s_cselect_b32 s26, s22, s67
	v_lshl_add_u64 v[222:223], s[24:25], 0, v[142:143]
	s_add_i32 m0, s30, 0xc000
	ds_read_b128 v[190:193], v160
	ds_read_b128 v[194:197], v160 offset:1024
	ds_read_b128 v[198:201], v160 offset:2048
	ds_read_b128 v[202:205], v160 offset:3072
	ds_read_b128 v[206:209], v160 offset:4096
	ds_read_b128 v[210:213], v160 offset:5120
	ds_read_b128 v[214:217], v160 offset:6144
	ds_read_b128 v[218:221], v160 offset:7168
	global_load_lds_dwordx4 v[222:223], off
	v_lshl_add_u64 v[222:223], s[24:25], 0, v[144:145]
	s_add_i32 m0, s30, 0xe000
	s_nop 0
	global_load_lds_dwordx4 v[222:223], off
	s_waitcnt vmcnt(8)
	s_waitcnt lgkmcnt(0)
	s_setprio 1
	s_barrier
	v_mfma_f32_16x16x32_bf16 v[124:127], v[150:153], v[190:193], v[124:127]
	v_mfma_f32_16x16x32_bf16 v[120:123], v[162:165], v[190:193], v[120:123]
	v_mfma_f32_16x16x32_bf16 v[116:119], v[150:153], v[198:201], v[116:119]
	v_mfma_f32_16x16x32_bf16 v[112:115], v[162:165], v[198:201], v[112:115]
	v_mfma_f32_16x16x32_bf16 v[108:111], v[150:153], v[206:209], v[108:111]
	v_mfma_f32_16x16x32_bf16 v[104:107], v[162:165], v[206:209], v[104:107]
	v_mfma_f32_16x16x32_bf16 v[100:103], v[150:153], v[214:217], v[100:103]
	v_mfma_f32_16x16x32_bf16 v[96:99], v[162:165], v[214:217], v[96:99]
	v_mfma_f32_16x16x32_bf16 v[124:127], v[154:157], v[194:197], v[124:127]
	v_mfma_f32_16x16x32_bf16 v[120:123], v[166:169], v[194:197], v[120:123]
	v_mfma_f32_16x16x32_bf16 v[116:119], v[154:157], v[202:205], v[116:119]
	v_mfma_f32_16x16x32_bf16 v[112:115], v[166:169], v[202:205], v[112:115]
	v_mfma_f32_16x16x32_bf16 v[108:111], v[154:157], v[210:213], v[108:111]
	v_mfma_f32_16x16x32_bf16 v[104:107], v[166:169], v[210:213], v[104:107]
	v_mfma_f32_16x16x32_bf16 v[100:103], v[154:157], v[218:221], v[100:103]
	v_mfma_f32_16x16x32_bf16 v[96:99], v[166:169], v[218:221], v[96:99]
	s_setprio 0
	s_setprio 1
	v_mfma_f32_16x16x32_bf16 v[60:63], v[174:177], v[190:193], v[60:63]
	v_mfma_f32_16x16x32_bf16 v[56:59], v[182:185], v[190:193], v[56:59]
	v_mfma_f32_16x16x32_bf16 v[52:55], v[174:177], v[198:201], v[52:55]
	v_mfma_f32_16x16x32_bf16 v[48:51], v[182:185], v[198:201], v[48:51]
	v_mfma_f32_16x16x32_bf16 v[44:47], v[174:177], v[206:209], v[44:47]
	v_mfma_f32_16x16x32_bf16 v[40:43], v[182:185], v[206:209], v[40:43]
	v_mfma_f32_16x16x32_bf16 v[36:39], v[174:177], v[214:217], v[36:39]
	v_mfma_f32_16x16x32_bf16 v[32:35], v[182:185], v[214:217], v[32:35]
	v_mfma_f32_16x16x32_bf16 v[60:63], v[178:181], v[194:197], v[60:63]
	v_mfma_f32_16x16x32_bf16 v[56:59], v[186:189], v[194:197], v[56:59]
	v_mfma_f32_16x16x32_bf16 v[52:55], v[178:181], v[202:205], v[52:55]
	v_mfma_f32_16x16x32_bf16 v[48:51], v[186:189], v[202:205], v[48:51]
	v_mfma_f32_16x16x32_bf16 v[44:47], v[178:181], v[210:213], v[44:47]
	v_mfma_f32_16x16x32_bf16 v[40:43], v[186:189], v[210:213], v[40:43]
	v_mfma_f32_16x16x32_bf16 v[36:39], v[178:181], v[218:221], v[36:39]
	v_mfma_f32_16x16x32_bf16 v[32:35], v[186:189], v[218:221], v[32:35]
	s_barrier
	s_setprio 0
	s_add_i32 s36, s52, s21
	v_lshl_add_u64 v[222:223], s[26:27], 0, v[130:131]
	s_mov_b32 m0, s36
	ds_read_b128 v[190:193], v160 offset:16384
	ds_read_b128 v[194:197], v160 offset:17408
	ds_read_b128 v[198:201], v160 offset:18432
	ds_read_b128 v[202:205], v160 offset:19456
	ds_read_b128 v[206:209], v160 offset:20480
	ds_read_b128 v[210:213], v160 offset:21504
	ds_read_b128 v[214:217], v160 offset:22528
	ds_read_b128 v[218:221], v160 offset:23552
	global_load_lds_dwordx4 v[222:223], off
	s_add_i32 m0, s36, 0x2000
	s_add_u32 s36, s26, 0x160000
	v_lshl_add_u64 v[224:225], s[26:27], 0, v[134:135]
	s_addc_u32 s37, s27, 0
	s_add_i32 s58, s53, s21
	global_load_lds_dwordx4 v[224:225], off
	v_lshl_add_u64 v[226:227], s[36:37], 0, v[130:131]
	s_mov_b32 m0, s58
	v_lshl_add_u64 v[228:229], s[28:29], 0, v[132:133]
	global_load_lds_dwordx4 v[226:227], off
	v_lshl_add_u64 v[226:227], s[36:37], 0, v[134:135]
	s_add_i32 m0, s58, 0x2000
	s_nop 0
	global_load_lds_dwordx4 v[226:227], off
	v_lshl_add_u64 v[226:227], s[28:29], 0, v[128:129]
	s_mov_b32 m0, s30
	s_nop 0
	global_load_lds_dwordx4 v[226:227], off
	s_mov_b32 m0, s31
	s_nop 0
	global_load_lds_dwordx4 v[228:229], off
	s_waitcnt vmcnt(8)
	s_waitcnt lgkmcnt(0)
	s_setprio 1
	s_barrier
; #define PG8_STAGE(bufoff, gbase, voff) do { _Pragma("unroll") for (int _i = 0; _i < 2; ++_i) \
;         __builtin_amdgcn_global_load_lds((const unsigned*)((const char*)(gbase) + (voff)[_i]), (PG8_LAS unsigned*)(lds + (bufoff) + ldsw + _i * 8192), 16, 0, 0); } while (0)
; #define PG8_LDA(dst, b, h) do { _Pragma("unroll") for (int m = 0; m < 4; ++m) _Pragma("unroll") for (int k = 0; k < 2; ++k) dst[m][k] = *(const PG8_LAS bf16x8*)(lds + PG8_SA(b, h) + aoff + m * 2048 + k * 1024); } while (0)
; #define PG8_LDB(dst, b, h) do { _Pragma("unroll") for (int n = 0; n < 2; ++n) _Pragma("unroll") for (int k = 0; k < 2; ++k) dst[n][k] = *(const PG8_LAS bf16x8*)(lds + PG8_SB(b, h) + boff + n * 2048 + k * 1024); } while (0)
; #define PG8_MMA(ai, bj, At, Bt) do { __builtin_amdgcn_s_setprio(1); _Pragma("unroll") for (int m = 0; m < 4; ++m) _Pragma("unroll") for (int n = 0; n < 2; ++n) _Pragma("unroll") for (int k = 0; k < 2; ++k) \
;         acc[ai][bj][m][n] = __builtin_amdgcn_mfma_f32_16x16x32_bf16(Bt[n][k], At[m][k], acc[ai][bj][m][n], 0, 0, 0); __builtin_amdgcn_s_setprio(0); } while (0)
; #define PG8_WAIT_V(n) asm volatile("s_waitcnt vmcnt(" #n ")" ::: "memory")
; #define PG8_WAIT_L(n) asm volatile("s_waitcnt lgkmcnt(" #n ")" ::: "memory")
; #define PG8_BAR __builtin_amdgcn_s_barrier()
; #define PG8_SCHED __builtin_amdgcn_sched_barrier(0)
; template <class Epi, class Sched, bool ALIGN_EPI = false, bool SP2 = false>
; __device__ __forceinline__ void gemm_phase(PG8_LAS unsigned char* lds, const Gemm g, const Sched& S, const Epi& E) {
;     ...
;             PG8_WAIT_V(8); PG8_WAIT_L(0); PG8_BAR; PG8_MMA(1, 0, At, B0); PG8_MMA(1, 1, At, B1); PG8_BAR; PG8_SCHED;
;             PG8_LDB(B0, 1, 0); PG8_LDB(B1, 1, 1); PG8_SCHED; PG8_LDA(At, 1, 0); PG8_STAGE(PG8_SA(0, 1), a2 + hstep, voffA);
;             PG8_WAIT_V(8); PG8_WAIT_L(0); PG8_BAR; PG8_MMA(0, 0, At, B0); PG8_MMA(0, 1, At, B1); PG8_BAR; PG8_SCHED;
	v_mfma_f32_16x16x32_bf16 v[92:95], v[150:153], v[190:193], v[92:95]
	v_mfma_f32_16x16x32_bf16 v[88:91], v[162:165], v[190:193], v[88:91]
	v_mfma_f32_16x16x32_bf16 v[84:87], v[150:153], v[198:201], v[84:87]
	v_mfma_f32_16x16x32_bf16 v[80:83], v[162:165], v[198:201], v[80:83]
	v_mfma_f32_16x16x32_bf16 v[76:79], v[150:153], v[206:209], v[76:79]
	v_mfma_f32_16x16x32_bf16 v[72:75], v[162:165], v[206:209], v[72:75]
	v_mfma_f32_16x16x32_bf16 v[68:71], v[150:153], v[214:217], v[68:71]
	v_mfma_f32_16x16x32_bf16 v[64:67], v[162:165], v[214:217], v[64:67]
	v_mfma_f32_16x16x32_bf16 v[92:95], v[154:157], v[194:197], v[92:95]
	v_mfma_f32_16x16x32_bf16 v[88:91], v[166:169], v[194:197], v[88:91]
	v_mfma_f32_16x16x32_bf16 v[84:87], v[154:157], v[202:205], v[84:87]
	v_mfma_f32_16x16x32_bf16 v[80:83], v[166:169], v[202:205], v[80:83]
	v_mfma_f32_16x16x32_bf16 v[76:79], v[154:157], v[210:213], v[76:79]
	v_mfma_f32_16x16x32_bf16 v[72:75], v[166:169], v[210:213], v[72:75]
	v_mfma_f32_16x16x32_bf16 v[68:71], v[154:157], v[218:221], v[68:71]
	v_mfma_f32_16x16x32_bf16 v[64:67], v[166:169], v[218:221], v[64:67]
	s_setprio 0
	s_setprio 1
	v_mfma_f32_16x16x32_bf16 v[28:31], v[174:177], v[190:193], v[28:31]
	v_mfma_f32_16x16x32_bf16 v[24:27], v[182:185], v[190:193], v[24:27]
	v_mfma_f32_16x16x32_bf16 v[20:23], v[174:177], v[198:201], v[20:23]
	v_mfma_f32_16x16x32_bf16 v[16:19], v[182:185], v[198:201], v[16:19]
	v_mfma_f32_16x16x32_bf16 v[12:15], v[174:177], v[206:209], v[12:15]
	v_mfma_f32_16x16x32_bf16 v[8:11], v[182:185], v[206:209], v[8:11]
	v_mfma_f32_16x16x32_bf16 v[4:7], v[174:177], v[214:217], v[4:7]
	v_mfma_f32_16x16x32_bf16 v[0:3], v[182:185], v[214:217], v[0:3]
	v_mfma_f32_16x16x32_bf16 v[28:31], v[178:181], v[194:197], v[28:31]
	v_mfma_f32_16x16x32_bf16 v[24:27], v[186:189], v[194:197], v[24:27]
	v_mfma_f32_16x16x32_bf16 v[20:23], v[178:181], v[202:205], v[20:23]
	v_mfma_f32_16x16x32_bf16 v[16:19], v[186:189], v[202:205], v[16:19]
	v_mfma_f32_16x16x32_bf16 v[12:15], v[178:181], v[210:213], v[12:15]
	v_mfma_f32_16x16x32_bf16 v[8:11], v[186:189], v[210:213], v[8:11]
	v_mfma_f32_16x16x32_bf16 v[4:7], v[178:181], v[218:221], v[4:7]
	v_mfma_f32_16x16x32_bf16 v[0:3], v[186:189], v[218:221], v[0:3]
	s_barrier
	s_setprio 0
	s_add_i32 s36, 0, 0x18000
	v_add_u32_e32 v140, s36, v137
	s_add_i32 s37, 0, 0x1c000
	ds_read_b128 v[150:153], v140
	ds_read_b128 v[154:157], v140 offset:1024
	ds_read_b128 v[162:165], v140 offset:2048
	ds_read_b128 v[166:169], v140 offset:3072
	v_add_u32_e32 v140, s37, v137
	ds_read_b128 v[174:177], v140
	ds_read_b128 v[178:181], v140 offset:1024
	ds_read_b128 v[182:185], v140 offset:2048
	ds_read_b128 v[186:189], v140 offset:3072
	s_add_u32 s28, s28, 0x160000
	s_addc_u32 s29, s29, 0
	s_mov_b32 m0, s34
	v_lshl_add_u64 v[230:231], s[28:29], 0, v[128:129]
	ds_read_b128 v[190:193], v160 offset:32768
	ds_read_b128 v[194:197], v160 offset:33792
	ds_read_b128 v[198:201], v160 offset:34816
	ds_read_b128 v[202:205], v160 offset:35840
	ds_read_b128 v[206:209], v160 offset:36864
	ds_read_b128 v[210:213], v160 offset:37888
	ds_read_b128 v[214:217], v160 offset:38912
	ds_read_b128 v[218:221], v160 offset:39936
	global_load_lds_dwordx4 v[230:231], off
	v_lshl_add_u64 v[230:231], s[28:29], 0, v[132:133]
	s_mov_b32 m0, s35
	s_nop 0
	global_load_lds_dwordx4 v[230:231], off
	s_waitcnt vmcnt(8)
	s_waitcnt lgkmcnt(0)
	s_setprio 1
	s_barrier
	v_mfma_f32_16x16x32_bf16 v[124:127], v[150:153], v[190:193], v[124:127]
	v_mfma_f32_16x16x32_bf16 v[120:123], v[162:165], v[190:193], v[120:123]
	v_mfma_f32_16x16x32_bf16 v[116:119], v[150:153], v[198:201], v[116:119]
	v_mfma_f32_16x16x32_bf16 v[112:115], v[162:165], v[198:201], v[112:115]
	v_mfma_f32_16x16x32_bf16 v[108:111], v[150:153], v[206:209], v[108:111]
	v_mfma_f32_16x16x32_bf16 v[104:107], v[162:165], v[206:209], v[104:107]
	v_mfma_f32_16x16x32_bf16 v[100:103], v[150:153], v[214:217], v[100:103]
	v_mfma_f32_16x16x32_bf16 v[96:99], v[162:165], v[214:217], v[96:99]
	v_mfma_f32_16x16x32_bf16 v[124:127], v[154:157], v[194:197], v[124:127]
	v_mfma_f32_16x16x32_bf16 v[120:123], v[166:169], v[194:197], v[120:123]
	v_mfma_f32_16x16x32_bf16 v[116:119], v[154:157], v[202:205], v[116:119]
	v_mfma_f32_16x16x32_bf16 v[112:115], v[166:169], v[202:205], v[112:115]
	v_mfma_f32_16x16x32_bf16 v[108:111], v[154:157], v[210:213], v[108:111]
	v_mfma_f32_16x16x32_bf16 v[104:107], v[166:169], v[210:213], v[104:107]
	v_mfma_f32_16x16x32_bf16 v[100:103], v[154:157], v[218:221], v[100:103]
	v_mfma_f32_16x16x32_bf16 v[96:99], v[166:169], v[218:221], v[96:99]
	s_setprio 0
	s_setprio 1
	v_mfma_f32_16x16x32_bf16 v[60:63], v[174:177], v[190:193], v[60:63]
	v_mfma_f32_16x16x32_bf16 v[56:59], v[182:185], v[190:193], v[56:59]
	v_mfma_f32_16x16x32_bf16 v[52:55], v[174:177], v[198:201], v[52:55]
	v_mfma_f32_16x16x32_bf16 v[48:51], v[182:185], v[198:201], v[48:51]
	v_mfma_f32_16x16x32_bf16 v[44:47], v[174:177], v[206:209], v[44:47]
	v_mfma_f32_16x16x32_bf16 v[40:43], v[182:185], v[206:209], v[40:43]
	v_mfma_f32_16x16x32_bf16 v[36:39], v[174:177], v[214:217], v[36:39]
	v_mfma_f32_16x16x32_bf16 v[32:35], v[182:185], v[214:217], v[32:35]
	v_mfma_f32_16x16x32_bf16 v[60:63], v[178:181], v[194:197], v[60:63]
	v_mfma_f32_16x16x32_bf16 v[56:59], v[186:189], v[194:197], v[56:59]
	v_mfma_f32_16x16x32_bf16 v[52:55], v[178:181], v[202:205], v[52:55]
	v_mfma_f32_16x16x32_bf16 v[48:51], v[186:189], v[202:205], v[48:51]
	v_mfma_f32_16x16x32_bf16 v[44:47], v[178:181], v[210:213], v[44:47]
	v_mfma_f32_16x16x32_bf16 v[40:43], v[186:189], v[210:213], v[40:43]
	v_mfma_f32_16x16x32_bf16 v[36:39], v[178:181], v[218:221], v[36:39]
	v_mfma_f32_16x16x32_bf16 v[32:35], v[186:189], v[218:221], v[32:35]
	s_barrier
; #define PG8_STAGE(bufoff, gbase, voff) do { _Pragma("unroll") for (int _i = 0; _i < 2; ++_i) \
;         __builtin_amdgcn_global_load_lds((const unsigned*)((const char*)(gbase) + (voff)[_i]), (PG8_LAS unsigned*)(lds + (bufoff) + ldsw + _i * 8192), 16, 0, 0); } while (0)
; #define PG8_LDA(dst, b, h) do { _Pragma("unroll") for (int m = 0; m < 4; ++m) _Pragma("unroll") for (int k = 0; k < 2; ++k) dst[m][k] = *(const PG8_LAS bf16x8*)(lds + PG8_SA(b, h) + aoff + m * 2048 + k * 1024); } while (0)
; #define PG8_MMA(ai, bj, At, Bt) do { __builtin_amdgcn_s_setprio(1); _Pragma("unroll") for (int m = 0; m < 4; ++m) _Pragma("unroll") for (int n = 0; n < 2; ++n) _Pragma("unroll") for (int k = 0; k < 2; ++k) \
;         acc[ai][bj][m][n] = __builtin_amdgcn_mfma_f32_16x16x32_bf16(Bt[n][k], At[m][k], acc[ai][bj][m][n], 0, 0, 0); __builtin_amdgcn_s_setprio(0); } while (0)
; #define PG8_WAIT_V(n) asm volatile("s_waitcnt vmcnt(" #n ")" ::: "memory")
; #define PG8_WAIT_L(n) asm volatile("s_waitcnt lgkmcnt(" #n ")" ::: "memory")
; #define PG8_BAR __builtin_amdgcn_s_barrier()
; #define PG8_SCHED __builtin_amdgcn_sched_barrier(0)
; template <class Epi, class Sched, bool ALIGN_EPI = false, bool SP2 = false>
; __device__ __forceinline__ void gemm_phase(PG8_LAS unsigned char* lds, const Gemm g, const Sched& S, const Epi& E) {
;     ...
;             PG8_LDA(At, 1, 1); PG8_STAGE(PG8_SB(1, 0), b3, voffB); PG8_STAGE(PG8_SB(1, 1), b3 + hstep, voffB); PG8_STAGE(PG8_SA(1, 0), a3, voffA);
;             PG8_WAIT_V(8); PG8_WAIT_L(0); PG8_BAR; PG8_MMA(1, 0, At, B0); PG8_MMA(1, 1, At, B1); PG8_BAR; PG8_SCHED;
;     ...
;         }
;         if constexpr (ALIGN_EPI) { if (wr == 0) PG8_BAR; }
	s_setprio 0
	s_add_i32 s28, s36, s21
	v_lshl_add_u64 v[222:223], v[222:223], 0, s[16:17]
	s_mov_b32 m0, s28
	ds_read_b128 v[190:193], v160 offset:49152
	ds_read_b128 v[194:197], v160 offset:50176
	ds_read_b128 v[198:201], v160 offset:51200
	ds_read_b128 v[202:205], v160 offset:52224
	ds_read_b128 v[206:209], v160 offset:53248
	ds_read_b128 v[210:213], v160 offset:54272
	ds_read_b128 v[214:217], v160 offset:55296
	ds_read_b128 v[218:221], v160 offset:56320
	global_load_lds_dwordx4 v[222:223], off
	s_add_i32 m0, s28, 0x2000
	s_add_u32 s26, s26, 0x160080
	v_lshl_add_u64 v[222:223], v[224:225], 0, s[16:17]
	s_addc_u32 s27, s27, 0
	s_add_i32 s28, s37, s21
	global_load_lds_dwordx4 v[222:223], off
	v_lshl_add_u64 v[222:223], s[26:27], 0, v[130:131]
	s_mov_b32 m0, s28
	s_nop 0
	global_load_lds_dwordx4 v[222:223], off
	v_lshl_add_u64 v[222:223], s[26:27], 0, v[134:135]
	s_add_i32 m0, s28, 0x2000
	s_nop 0
	global_load_lds_dwordx4 v[222:223], off
	v_lshl_add_u64 v[222:223], v[226:227], 0, s[16:17]
	s_mov_b32 m0, s48
	s_nop 0
	global_load_lds_dwordx4 v[222:223], off
	v_lshl_add_u64 v[222:223], v[228:229], 0, s[16:17]
	s_mov_b32 m0, s49
	s_nop 0
	global_load_lds_dwordx4 v[222:223], off
	s_waitcnt vmcnt(8)
	s_waitcnt lgkmcnt(0)
	s_setprio 1
	s_barrier
	v_mfma_f32_16x16x32_bf16 v[92:95], v[150:153], v[190:193], v[92:95]
	v_mfma_f32_16x16x32_bf16 v[88:91], v[162:165], v[190:193], v[88:91]
	v_mfma_f32_16x16x32_bf16 v[84:87], v[150:153], v[198:201], v[84:87]
	v_mfma_f32_16x16x32_bf16 v[80:83], v[162:165], v[198:201], v[80:83]
	v_mfma_f32_16x16x32_bf16 v[76:79], v[150:153], v[206:209], v[76:79]
	v_mfma_f32_16x16x32_bf16 v[72:75], v[162:165], v[206:209], v[72:75]
	v_mfma_f32_16x16x32_bf16 v[68:71], v[150:153], v[214:217], v[68:71]
	v_mfma_f32_16x16x32_bf16 v[64:67], v[162:165], v[214:217], v[64:67]
	v_mfma_f32_16x16x32_bf16 v[92:95], v[154:157], v[194:197], v[92:95]
	v_mfma_f32_16x16x32_bf16 v[88:91], v[166:169], v[194:197], v[88:91]
	v_mfma_f32_16x16x32_bf16 v[84:87], v[154:157], v[202:205], v[84:87]
	v_mfma_f32_16x16x32_bf16 v[80:83], v[166:169], v[202:205], v[80:83]
	v_mfma_f32_16x16x32_bf16 v[76:79], v[154:157], v[210:213], v[76:79]
	v_mfma_f32_16x16x32_bf16 v[72:75], v[166:169], v[210:213], v[72:75]
	v_mfma_f32_16x16x32_bf16 v[68:71], v[154:157], v[218:221], v[68:71]
	v_mfma_f32_16x16x32_bf16 v[64:67], v[166:169], v[218:221], v[64:67]
	s_setprio 0
	s_setprio 1
	v_mfma_f32_16x16x32_bf16 v[28:31], v[174:177], v[190:193], v[28:31]
	v_mfma_f32_16x16x32_bf16 v[24:27], v[182:185], v[190:193], v[24:27]
	v_mfma_f32_16x16x32_bf16 v[20:23], v[174:177], v[198:201], v[20:23]
	v_mfma_f32_16x16x32_bf16 v[16:19], v[182:185], v[198:201], v[16:19]
	v_mfma_f32_16x16x32_bf16 v[12:15], v[174:177], v[206:209], v[12:15]
	v_mfma_f32_16x16x32_bf16 v[8:11], v[182:185], v[206:209], v[8:11]
	v_mfma_f32_16x16x32_bf16 v[4:7], v[174:177], v[214:217], v[4:7]
	v_mfma_f32_16x16x32_bf16 v[0:3], v[182:185], v[214:217], v[0:3]
	v_mfma_f32_16x16x32_bf16 v[28:31], v[178:181], v[194:197], v[28:31]
	v_mfma_f32_16x16x32_bf16 v[24:27], v[186:189], v[194:197], v[24:27]
	v_mfma_f32_16x16x32_bf16 v[20:23], v[178:181], v[202:205], v[20:23]
	v_mfma_f32_16x16x32_bf16 v[16:19], v[186:189], v[202:205], v[16:19]
	v_mfma_f32_16x16x32_bf16 v[12:15], v[178:181], v[210:213], v[12:15]
	v_mfma_f32_16x16x32_bf16 v[8:11], v[186:189], v[210:213], v[8:11]
	v_mfma_f32_16x16x32_bf16 v[4:7], v[178:181], v[218:221], v[4:7]
	v_mfma_f32_16x16x32_bf16 v[0:3], v[186:189], v[218:221], v[0:3]
	s_barrier
	s_setprio 0
	s_add_i32 s73, s73, 2
	s_add_u32 s24, s24, 0x100
	s_addc_u32 s25, s25, 0
	s_add_u32 s67, s67, 0x100
	s_addc_u32 s72, s72, 0
	s_cmpk_gt_u32 s73, 0x55
	s_cbranch_scc0 .LBB0_606
	s_and_b64 vcc, exec, s[18:19]
	s_cbranch_vccz .LBB0_609
	s_barrier

; #define PG8_STAGE(bufoff, gbase, voff) do { _Pragma("unroll") for (int _i = 0; _i < 2; ++_i) \
;         __builtin_amdgcn_global_load_lds((const unsigned*)((const char*)(gbase) + (voff)[_i]), (PG8_LAS unsigned*)(lds + (bufoff) + ldsw + _i * 8192), 16, 0, 0); } while (0)
; #define PG8_LDA(dst, b, h) do { _Pragma("unroll") for (int m = 0; m < 4; ++m) _Pragma("unroll") for (int k = 0; k < 2; ++k) dst[m][k] = *(const PG8_LAS bf16x8*)(lds + PG8_SA(b, h) + aoff + m * 2048 + k * 1024); } while (0)
; #define PG8_LDB(dst, b, h) do { _Pragma("unroll") for (int n = 0; n < 2; ++n) _Pragma("unroll") for (int k = 0; k < 2; ++k) dst[n][k] = *(const PG8_LAS bf16x8*)(lds + PG8_SB(b, h) + boff + n * 2048 + k * 1024); } while (0)
; #define PG8_MMA(ai, bj, At, Bt) do { __builtin_amdgcn_s_setprio(1); _Pragma("unroll") for (int m = 0; m < 4; ++m) _Pragma("unroll") for (int n = 0; n < 2; ++n) _Pragma("unroll") for (int k = 0; k < 2; ++k) \
;         acc[ai][bj][m][n] = __builtin_amdgcn_mfma_f32_16x16x32_bf16(Bt[n][k], At[m][k], acc[ai][bj][m][n], 0, 0, 0); __builtin_amdgcn_s_setprio(0); } while (0)
; #define PG8_WAIT_V(n) asm volatile("s_waitcnt vmcnt(" #n ")" ::: "memory")
; #define PG8_WAIT_L(n) asm volatile("s_waitcnt lgkmcnt(" #n ")" ::: "memory")
; #define PG8_BAR __builtin_amdgcn_s_barrier()
; #define PG8_SCHED __builtin_amdgcn_sched_barrier(0)
; template <class Epi, class Sched, bool ALIGN_EPI = false, bool SP2 = false>
; __device__ __forceinline__ void gemm_phase(PG8_LAS unsigned char* lds, const Gemm g, const Sched& S, const Epi& E) {
;     ...
;             PG8_LDB(B0, 0, 0); PG8_LDB(B1, 0, 1); PG8_SCHED; PG8_LDA(At, 0, 0); PG8_STAGE(PG8_SA(1, 1), a1 + hstep, voffA);
;             PG8_WAIT_V(8); PG8_WAIT_L(0); PG8_BAR; PG8_MMA(0, 0, At, B0); PG8_MMA(0, 1, At, B1); PG8_BAR; PG8_SCHED;
;             PG8_LDA(At, 0, 1); PG8_STAGE(PG8_SB(0, 0), b2, voffB); PG8_STAGE(PG8_SB(0, 1), b2 + hstep, voffB); PG8_STAGE(PG8_SA(0, 0), a2, voffA);
;             PG8_WAIT_V(8); PG8_WAIT_L(0); PG8_BAR; PG8_MMA(1, 0, At, B0); PG8_MMA(1, 1, At, B1); PG8_BAR; PG8_SCHED;
.LBB0_744:
	ds_read_b128 v[112:115], v174
	ds_read_b128 v[116:119], v174 offset:1024
	ds_read_b128 v[158:161], v174 offset:2048
	ds_read_b128 v[162:165], v174 offset:3072
	ds_read_b128 v[166:169], v175
	ds_read_b128 v[178:181], v175 offset:1024
	ds_read_b128 v[182:185], v175 offset:2048
	ds_read_b128 v[186:189], v175 offset:3072
	s_add_u32 s36, s34, 0xfff80080
	s_addc_u32 s37, s35, -1
	s_cmp_eq_u32 s75, 28
	s_cselect_b32 s51, s25, s37
	s_cselect_b32 s50, s71, s36
	s_cselect_b32 s49, s23, s74
	s_cselect_b32 s48, s72, s73
	v_lshl_add_u64 v[170:171], s[34:35], 0, v[150:151]
	s_add_i32 m0, s31, 0xc000
	ds_read_b128 v[190:193], v176
	ds_read_b128 v[194:197], v176 offset:1024
	ds_read_b128 v[198:201], v176 offset:2048
	ds_read_b128 v[202:205], v176 offset:3072
	ds_read_b128 v[206:209], v176 offset:4096
	ds_read_b128 v[210:213], v176 offset:5120
	ds_read_b128 v[214:217], v176 offset:6144
	ds_read_b128 v[218:221], v176 offset:7168
	global_load_lds_dwordx4 v[170:171], off
	v_lshl_add_u64 v[170:171], s[34:35], 0, v[152:153]
	s_add_i32 m0, s31, 0xe000
	s_nop 0
	global_load_lds_dwordx4 v[170:171], off
	s_waitcnt vmcnt(8)
	s_waitcnt lgkmcnt(0)
	s_setprio 1
	s_barrier
	v_mfma_f32_16x16x32_bf16 v[132:135], v[112:115], v[190:193], v[132:135]
	v_mfma_f32_16x16x32_bf16 v[128:131], v[158:161], v[190:193], v[128:131]
	v_mfma_f32_16x16x32_bf16 v[124:127], v[112:115], v[198:201], v[124:127]
	v_mfma_f32_16x16x32_bf16 v[120:123], v[158:161], v[198:201], v[120:123]
	v_mfma_f32_16x16x32_bf16 v[108:111], v[112:115], v[206:209], v[108:111]
	v_mfma_f32_16x16x32_bf16 v[104:107], v[158:161], v[206:209], v[104:107]
	v_mfma_f32_16x16x32_bf16 v[100:103], v[112:115], v[214:217], v[100:103]
	v_mfma_f32_16x16x32_bf16 v[96:99], v[158:161], v[214:217], v[96:99]
	v_mfma_f32_16x16x32_bf16 v[132:135], v[116:119], v[194:197], v[132:135]
	v_mfma_f32_16x16x32_bf16 v[128:131], v[162:165], v[194:197], v[128:131]
	v_mfma_f32_16x16x32_bf16 v[124:127], v[116:119], v[202:205], v[124:127]
	v_mfma_f32_16x16x32_bf16 v[120:123], v[162:165], v[202:205], v[120:123]
	v_mfma_f32_16x16x32_bf16 v[108:111], v[116:119], v[210:213], v[108:111]
	v_mfma_f32_16x16x32_bf16 v[104:107], v[162:165], v[210:213], v[104:107]
	v_mfma_f32_16x16x32_bf16 v[100:103], v[116:119], v[218:221], v[100:103]
	v_mfma_f32_16x16x32_bf16 v[96:99], v[162:165], v[218:221], v[96:99]
	s_setprio 0
	s_setprio 1
	v_mfma_f32_16x16x32_bf16 v[60:63], v[166:169], v[190:193], v[60:63]
	v_mfma_f32_16x16x32_bf16 v[56:59], v[182:185], v[190:193], v[56:59]
	v_mfma_f32_16x16x32_bf16 v[52:55], v[166:169], v[198:201], v[52:55]
	v_mfma_f32_16x16x32_bf16 v[48:51], v[182:185], v[198:201], v[48:51]
	v_mfma_f32_16x16x32_bf16 v[44:47], v[166:169], v[206:209], v[44:47]
	v_mfma_f32_16x16x32_bf16 v[40:43], v[182:185], v[206:209], v[40:43]
	v_mfma_f32_16x16x32_bf16 v[36:39], v[166:169], v[214:217], v[36:39]
	v_mfma_f32_16x16x32_bf16 v[32:35], v[182:185], v[214:217], v[32:35]
	v_mfma_f32_16x16x32_bf16 v[60:63], v[178:181], v[194:197], v[60:63]
	v_mfma_f32_16x16x32_bf16 v[56:59], v[186:189], v[194:197], v[56:59]
	v_mfma_f32_16x16x32_bf16 v[52:55], v[178:181], v[202:205], v[52:55]
	v_mfma_f32_16x16x32_bf16 v[48:51], v[186:189], v[202:205], v[48:51]
	v_mfma_f32_16x16x32_bf16 v[44:47], v[178:181], v[210:213], v[44:47]
	v_mfma_f32_16x16x32_bf16 v[40:43], v[186:189], v[210:213], v[40:43]
	v_mfma_f32_16x16x32_bf16 v[36:39], v[178:181], v[218:221], v[36:39]
	v_mfma_f32_16x16x32_bf16 v[32:35], v[186:189], v[218:221], v[32:35]
	s_barrier
	s_setprio 0
	s_add_i32 s36, s66, s21
	v_lshl_add_u64 v[170:171], s[48:49], 0, v[142:143]
	s_mov_b32 m0, s36
	ds_read_b128 v[190:193], v176 offset:16384
	ds_read_b128 v[194:197], v176 offset:17408
	ds_read_b128 v[198:201], v176 offset:18432
	ds_read_b128 v[202:205], v176 offset:19456
	ds_read_b128 v[206:209], v176 offset:20480
	ds_read_b128 v[210:213], v176 offset:21504
	ds_read_b128 v[214:217], v176 offset:22528
	ds_read_b128 v[218:221], v176 offset:23552
	global_load_lds_dwordx4 v[170:171], off
	s_add_i32 m0, s36, 0x2000
	s_add_u32 s36, s48, 0x80000
	v_lshl_add_u64 v[222:223], s[48:49], 0, v[146:147]
	s_addc_u32 s37, s49, 0
	s_add_i32 s58, s67, s21
	global_load_lds_dwordx4 v[222:223], off
	v_lshl_add_u64 v[224:225], s[36:37], 0, v[142:143]
	s_mov_b32 m0, s58
	v_lshl_add_u64 v[226:227], s[50:51], 0, v[144:145]
	global_load_lds_dwordx4 v[224:225], off
	v_lshl_add_u64 v[224:225], s[36:37], 0, v[146:147]
	s_add_i32 m0, s58, 0x2000
	s_nop 0
	global_load_lds_dwordx4 v[224:225], off
	v_lshl_add_u64 v[224:225], s[50:51], 0, v[140:141]
	s_mov_b32 m0, s31
	s_nop 0
	global_load_lds_dwordx4 v[224:225], off
	s_mov_b32 m0, s39
	s_nop 0
	global_load_lds_dwordx4 v[226:227], off
	s_waitcnt vmcnt(8)
	s_waitcnt lgkmcnt(0)
	s_setprio 1
	s_barrier
; #define PG8_STAGE(bufoff, gbase, voff) do { _Pragma("unroll") for (int _i = 0; _i < 2; ++_i) \
;         __builtin_amdgcn_global_load_lds((const unsigned*)((const char*)(gbase) + (voff)[_i]), (PG8_LAS unsigned*)(lds + (bufoff) + ldsw + _i * 8192), 16, 0, 0); } while (0)
; #define PG8_LDA(dst, b, h) do { _Pragma("unroll") for (int m = 0; m < 4; ++m) _Pragma("unroll") for (int k = 0; k < 2; ++k) dst[m][k] = *(const PG8_LAS bf16x8*)(lds + PG8_SA(b, h) + aoff + m * 2048 + k * 1024); } while (0)
; #define PG8_LDB(dst, b, h) do { _Pragma("unroll") for (int n = 0; n < 2; ++n) _Pragma("unroll") for (int k = 0; k < 2; ++k) dst[n][k] = *(const PG8_LAS bf16x8*)(lds + PG8_SB(b, h) + boff + n * 2048 + k * 1024); } while (0)
; #define PG8_MMA(ai, bj, At, Bt) do { __builtin_amdgcn_s_setprio(1); _Pragma("unroll") for (int m = 0; m < 4; ++m) _Pragma("unroll") for (int n = 0; n < 2; ++n) _Pragma("unroll") for (int k = 0; k < 2; ++k) \
;         acc[ai][bj][m][n] = __builtin_amdgcn_mfma_f32_16x16x32_bf16(Bt[n][k], At[m][k], acc[ai][bj][m][n], 0, 0, 0); __builtin_amdgcn_s_setprio(0); } while (0)
; #define PG8_WAIT_V(n) asm volatile("s_waitcnt vmcnt(" #n ")" ::: "memory")
; #define PG8_WAIT_L(n) asm volatile("s_waitcnt lgkmcnt(" #n ")" ::: "memory")
; #define PG8_BAR __builtin_amdgcn_s_barrier()
; #define PG8_SCHED __builtin_amdgcn_sched_barrier(0)
; template <class Epi, class Sched, bool ALIGN_EPI = false, bool SP2 = false>
; __device__ __forceinline__ void gemm_phase(PG8_LAS unsigned char* lds, const Gemm g, const Sched& S, const Epi& E) {
;     ...
;             PG8_WAIT_V(8); PG8_WAIT_L(0); PG8_BAR; PG8_MMA(1, 0, At, B0); PG8_MMA(1, 1, At, B1); PG8_BAR; PG8_SCHED;
;             PG8_LDB(B0, 1, 0); PG8_LDB(B1, 1, 1); PG8_SCHED; PG8_LDA(At, 1, 0); PG8_STAGE(PG8_SA(0, 1), a2 + hstep, voffA);
;             PG8_WAIT_V(8); PG8_WAIT_L(0); PG8_BAR; PG8_MMA(0, 0, At, B0); PG8_MMA(0, 1, At, B1); PG8_BAR; PG8_SCHED;
	v_mfma_f32_16x16x32_bf16 v[92:95], v[112:115], v[190:193], v[92:95]
	v_mfma_f32_16x16x32_bf16 v[88:91], v[158:161], v[190:193], v[88:91]
	v_mfma_f32_16x16x32_bf16 v[84:87], v[112:115], v[198:201], v[84:87]
	v_mfma_f32_16x16x32_bf16 v[80:83], v[158:161], v[198:201], v[80:83]
	v_mfma_f32_16x16x32_bf16 v[76:79], v[112:115], v[206:209], v[76:79]
	v_mfma_f32_16x16x32_bf16 v[72:75], v[158:161], v[206:209], v[72:75]
	v_mfma_f32_16x16x32_bf16 v[68:71], v[112:115], v[214:217], v[68:71]
	v_mfma_f32_16x16x32_bf16 v[64:67], v[158:161], v[214:217], v[64:67]
	v_mfma_f32_16x16x32_bf16 v[92:95], v[116:119], v[194:197], v[92:95]
	v_mfma_f32_16x16x32_bf16 v[88:91], v[162:165], v[194:197], v[88:91]
	v_mfma_f32_16x16x32_bf16 v[84:87], v[116:119], v[202:205], v[84:87]
	v_mfma_f32_16x16x32_bf16 v[80:83], v[162:165], v[202:205], v[80:83]
	v_mfma_f32_16x16x32_bf16 v[76:79], v[116:119], v[210:213], v[76:79]
	v_mfma_f32_16x16x32_bf16 v[72:75], v[162:165], v[210:213], v[72:75]
	v_mfma_f32_16x16x32_bf16 v[68:71], v[116:119], v[218:221], v[68:71]
	v_mfma_f32_16x16x32_bf16 v[64:67], v[162:165], v[218:221], v[64:67]
	s_setprio 0
	s_setprio 1
	v_mfma_f32_16x16x32_bf16 v[28:31], v[166:169], v[190:193], v[28:31]
	v_mfma_f32_16x16x32_bf16 v[24:27], v[182:185], v[190:193], v[24:27]
	v_mfma_f32_16x16x32_bf16 v[20:23], v[166:169], v[198:201], v[20:23]
	v_mfma_f32_16x16x32_bf16 v[16:19], v[182:185], v[198:201], v[16:19]
	v_mfma_f32_16x16x32_bf16 v[12:15], v[166:169], v[206:209], v[12:15]
	v_mfma_f32_16x16x32_bf16 v[8:11], v[182:185], v[206:209], v[8:11]
	v_mfma_f32_16x16x32_bf16 v[4:7], v[166:169], v[214:217], v[4:7]
	v_mfma_f32_16x16x32_bf16 v[0:3], v[182:185], v[214:217], v[0:3]
	v_mfma_f32_16x16x32_bf16 v[28:31], v[178:181], v[194:197], v[28:31]
	v_mfma_f32_16x16x32_bf16 v[24:27], v[186:189], v[194:197], v[24:27]
	v_mfma_f32_16x16x32_bf16 v[20:23], v[178:181], v[202:205], v[20:23]
	v_mfma_f32_16x16x32_bf16 v[16:19], v[186:189], v[202:205], v[16:19]
	v_mfma_f32_16x16x32_bf16 v[12:15], v[178:181], v[210:213], v[12:15]
	v_mfma_f32_16x16x32_bf16 v[8:11], v[186:189], v[210:213], v[8:11]
	v_mfma_f32_16x16x32_bf16 v[4:7], v[178:181], v[218:221], v[4:7]
	v_mfma_f32_16x16x32_bf16 v[0:3], v[186:189], v[218:221], v[0:3]
	s_barrier
	s_setprio 0
	s_add_i32 s58, 0, 0x18000
	v_add_u32_e32 v148, s58, v137
	s_add_i32 s59, 0, 0x1c000
	ds_read_b128 v[112:115], v148
	ds_read_b128 v[116:119], v148 offset:1024
	ds_read_b128 v[158:161], v148 offset:2048
	ds_read_b128 v[162:165], v148 offset:3072
	v_add_u32_e32 v148, s59, v137
	ds_read_b128 v[166:169], v148
	ds_read_b128 v[178:181], v148 offset:1024
	ds_read_b128 v[182:185], v148 offset:2048
	ds_read_b128 v[186:189], v148 offset:3072
	s_add_u32 s36, s50, 0x80000
	s_addc_u32 s37, s51, 0
	s_mov_b32 m0, s52
	v_lshl_add_u64 v[228:229], s[36:37], 0, v[140:141]
	ds_read_b128 v[190:193], v176 offset:32768
	ds_read_b128 v[194:197], v176 offset:33792
	ds_read_b128 v[198:201], v176 offset:34816
	ds_read_b128 v[202:205], v176 offset:35840
	ds_read_b128 v[206:209], v176 offset:36864
	ds_read_b128 v[210:213], v176 offset:37888
	ds_read_b128 v[214:217], v176 offset:38912
	ds_read_b128 v[218:221], v176 offset:39936
	global_load_lds_dwordx4 v[228:229], off
	v_lshl_add_u64 v[228:229], s[36:37], 0, v[144:145]
	s_mov_b32 m0, s53
	s_nop 0
	global_load_lds_dwordx4 v[228:229], off
	s_waitcnt vmcnt(8)
	s_waitcnt lgkmcnt(0)
	s_setprio 1
	s_barrier
	v_mfma_f32_16x16x32_bf16 v[132:135], v[112:115], v[190:193], v[132:135]
	v_mfma_f32_16x16x32_bf16 v[128:131], v[158:161], v[190:193], v[128:131]
	v_mfma_f32_16x16x32_bf16 v[124:127], v[112:115], v[198:201], v[124:127]
	v_mfma_f32_16x16x32_bf16 v[120:123], v[158:161], v[198:201], v[120:123]
	v_mfma_f32_16x16x32_bf16 v[108:111], v[112:115], v[206:209], v[108:111]
	v_mfma_f32_16x16x32_bf16 v[104:107], v[158:161], v[206:209], v[104:107]
	v_mfma_f32_16x16x32_bf16 v[100:103], v[112:115], v[214:217], v[100:103]
	v_mfma_f32_16x16x32_bf16 v[96:99], v[158:161], v[214:217], v[96:99]
	v_mfma_f32_16x16x32_bf16 v[132:135], v[116:119], v[194:197], v[132:135]
	v_mfma_f32_16x16x32_bf16 v[128:131], v[162:165], v[194:197], v[128:131]
	v_mfma_f32_16x16x32_bf16 v[124:127], v[116:119], v[202:205], v[124:127]
	v_mfma_f32_16x16x32_bf16 v[120:123], v[162:165], v[202:205], v[120:123]
	v_mfma_f32_16x16x32_bf16 v[108:111], v[116:119], v[210:213], v[108:111]
	v_mfma_f32_16x16x32_bf16 v[104:107], v[162:165], v[210:213], v[104:107]
	v_mfma_f32_16x16x32_bf16 v[100:103], v[116:119], v[218:221], v[100:103]
	v_mfma_f32_16x16x32_bf16 v[96:99], v[162:165], v[218:221], v[96:99]
	s_setprio 0
	s_setprio 1
	v_mfma_f32_16x16x32_bf16 v[60:63], v[166:169], v[190:193], v[60:63]
	v_mfma_f32_16x16x32_bf16 v[56:59], v[182:185], v[190:193], v[56:59]
	v_mfma_f32_16x16x32_bf16 v[52:55], v[166:169], v[198:201], v[52:55]
	v_mfma_f32_16x16x32_bf16 v[48:51], v[182:185], v[198:201], v[48:51]
	v_mfma_f32_16x16x32_bf16 v[44:47], v[166:169], v[206:209], v[44:47]
	v_mfma_f32_16x16x32_bf16 v[40:43], v[182:185], v[206:209], v[40:43]
	v_mfma_f32_16x16x32_bf16 v[36:39], v[166:169], v[214:217], v[36:39]
	v_mfma_f32_16x16x32_bf16 v[32:35], v[182:185], v[214:217], v[32:35]
	v_mfma_f32_16x16x32_bf16 v[60:63], v[178:181], v[194:197], v[60:63]
	v_mfma_f32_16x16x32_bf16 v[56:59], v[186:189], v[194:197], v[56:59]
	v_mfma_f32_16x16x32_bf16 v[52:55], v[178:181], v[202:205], v[52:55]
	v_mfma_f32_16x16x32_bf16 v[48:51], v[186:189], v[202:205], v[48:51]
	v_mfma_f32_16x16x32_bf16 v[44:47], v[178:181], v[210:213], v[44:47]
	v_mfma_f32_16x16x32_bf16 v[40:43], v[186:189], v[210:213], v[40:43]
	v_mfma_f32_16x16x32_bf16 v[36:39], v[178:181], v[218:221], v[36:39]
	v_mfma_f32_16x16x32_bf16 v[32:35], v[186:189], v[218:221], v[32:35]
	s_barrier
; #define PG8_STAGE(bufoff, gbase, voff) do { _Pragma("unroll") for (int _i = 0; _i < 2; ++_i) \
;         __builtin_amdgcn_global_load_lds((const unsigned*)((const char*)(gbase) + (voff)[_i]), (PG8_LAS unsigned*)(lds + (bufoff) + ldsw + _i * 8192), 16, 0, 0); } while (0)
; #define PG8_LDA(dst, b, h) do { _Pragma("unroll") for (int m = 0; m < 4; ++m) _Pragma("unroll") for (int k = 0; k < 2; ++k) dst[m][k] = *(const PG8_LAS bf16x8*)(lds + PG8_SA(b, h) + aoff + m * 2048 + k * 1024); } while (0)
; #define PG8_MMA(ai, bj, At, Bt) do { __builtin_amdgcn_s_setprio(1); _Pragma("unroll") for (int m = 0; m < 4; ++m) _Pragma("unroll") for (int n = 0; n < 2; ++n) _Pragma("unroll") for (int k = 0; k < 2; ++k) \
;         acc[ai][bj][m][n] = __builtin_amdgcn_mfma_f32_16x16x32_bf16(Bt[n][k], At[m][k], acc[ai][bj][m][n], 0, 0, 0); __builtin_amdgcn_s_setprio(0); } while (0)
; #define PG8_WAIT_V(n) asm volatile("s_waitcnt vmcnt(" #n ")" ::: "memory")
; #define PG8_WAIT_L(n) asm volatile("s_waitcnt lgkmcnt(" #n ")" ::: "memory")
; #define PG8_BAR __builtin_amdgcn_s_barrier()
; #define PG8_SCHED __builtin_amdgcn_sched_barrier(0)
; template <class Epi, class Sched, bool ALIGN_EPI = false, bool SP2 = false>
; __device__ __forceinline__ void gemm_phase(PG8_LAS unsigned char* lds, const Gemm g, const Sched& S, const Epi& E) {
;     ...
;             PG8_LDA(At, 1, 1); PG8_STAGE(PG8_SB(1, 0), b3, voffB); PG8_STAGE(PG8_SB(1, 1), b3 + hstep, voffB); PG8_STAGE(PG8_SA(1, 0), a3, voffA);
;             PG8_WAIT_V(8); PG8_WAIT_L(0); PG8_BAR; PG8_MMA(1, 0, At, B0); PG8_MMA(1, 1, At, B1); PG8_BAR; PG8_SCHED;
;     ...
;         }
;         if constexpr (ALIGN_EPI) { if (wr == 0) PG8_BAR; }
	s_setprio 0
	s_add_i32 s36, s58, s21
	v_lshl_add_u64 v[170:171], v[170:171], 0, s[16:17]
	s_mov_b32 m0, s36
	ds_read_b128 v[190:193], v176 offset:49152
	ds_read_b128 v[194:197], v176 offset:50176
	ds_read_b128 v[198:201], v176 offset:51200
	ds_read_b128 v[202:205], v176 offset:52224
	ds_read_b128 v[206:209], v176 offset:53248
	ds_read_b128 v[210:213], v176 offset:54272
	ds_read_b128 v[214:217], v176 offset:55296
	ds_read_b128 v[218:221], v176 offset:56320
	global_load_lds_dwordx4 v[170:171], off
	s_add_i32 m0, s36, 0x2000
	s_add_u32 s36, s48, 0x80080
	v_lshl_add_u64 v[170:171], v[222:223], 0, s[16:17]
	s_addc_u32 s37, s49, 0
	s_add_i32 s48, s59, s21
	global_load_lds_dwordx4 v[170:171], off
	v_lshl_add_u64 v[170:171], s[36:37], 0, v[142:143]
	s_mov_b32 m0, s48
	s_nop 0
	global_load_lds_dwordx4 v[170:171], off
	v_lshl_add_u64 v[170:171], s[36:37], 0, v[146:147]
	s_add_i32 m0, s48, 0x2000
	s_nop 0
	global_load_lds_dwordx4 v[170:171], off
	v_lshl_add_u64 v[170:171], v[224:225], 0, s[16:17]
	s_mov_b32 m0, s55
	s_nop 0
	global_load_lds_dwordx4 v[170:171], off
	v_lshl_add_u64 v[170:171], v[226:227], 0, s[16:17]
	s_mov_b32 m0, s57
	s_nop 0
	global_load_lds_dwordx4 v[170:171], off
	s_waitcnt vmcnt(8)
	s_waitcnt lgkmcnt(0)
	s_setprio 1
	s_barrier
	v_mfma_f32_16x16x32_bf16 v[92:95], v[112:115], v[190:193], v[92:95]
	v_mfma_f32_16x16x32_bf16 v[88:91], v[158:161], v[190:193], v[88:91]
	v_mfma_f32_16x16x32_bf16 v[84:87], v[112:115], v[198:201], v[84:87]
	v_mfma_f32_16x16x32_bf16 v[80:83], v[158:161], v[198:201], v[80:83]
	v_mfma_f32_16x16x32_bf16 v[76:79], v[112:115], v[206:209], v[76:79]
	v_mfma_f32_16x16x32_bf16 v[72:75], v[158:161], v[206:209], v[72:75]
	v_mfma_f32_16x16x32_bf16 v[68:71], v[112:115], v[214:217], v[68:71]
	v_mfma_f32_16x16x32_bf16 v[64:67], v[158:161], v[214:217], v[64:67]
	v_mfma_f32_16x16x32_bf16 v[92:95], v[116:119], v[194:197], v[92:95]
	v_mfma_f32_16x16x32_bf16 v[88:91], v[162:165], v[194:197], v[88:91]
	v_mfma_f32_16x16x32_bf16 v[84:87], v[116:119], v[202:205], v[84:87]
	v_mfma_f32_16x16x32_bf16 v[80:83], v[162:165], v[202:205], v[80:83]
	v_mfma_f32_16x16x32_bf16 v[76:79], v[116:119], v[210:213], v[76:79]
	v_mfma_f32_16x16x32_bf16 v[72:75], v[162:165], v[210:213], v[72:75]
	v_mfma_f32_16x16x32_bf16 v[68:71], v[116:119], v[218:221], v[68:71]
	v_mfma_f32_16x16x32_bf16 v[64:67], v[162:165], v[218:221], v[64:67]
	s_setprio 0
	s_setprio 1
	v_mfma_f32_16x16x32_bf16 v[28:31], v[166:169], v[190:193], v[28:31]
	v_mfma_f32_16x16x32_bf16 v[24:27], v[182:185], v[190:193], v[24:27]
	v_mfma_f32_16x16x32_bf16 v[20:23], v[166:169], v[198:201], v[20:23]
	v_mfma_f32_16x16x32_bf16 v[16:19], v[182:185], v[198:201], v[16:19]
	v_mfma_f32_16x16x32_bf16 v[12:15], v[166:169], v[206:209], v[12:15]
	v_mfma_f32_16x16x32_bf16 v[8:11], v[182:185], v[206:209], v[8:11]
	v_mfma_f32_16x16x32_bf16 v[4:7], v[166:169], v[214:217], v[4:7]
	v_mfma_f32_16x16x32_bf16 v[0:3], v[182:185], v[214:217], v[0:3]
	v_mfma_f32_16x16x32_bf16 v[28:31], v[178:181], v[194:197], v[28:31]
	v_mfma_f32_16x16x32_bf16 v[24:27], v[186:189], v[194:197], v[24:27]
	v_mfma_f32_16x16x32_bf16 v[20:23], v[178:181], v[202:205], v[20:23]
	v_mfma_f32_16x16x32_bf16 v[16:19], v[186:189], v[202:205], v[16:19]
	v_mfma_f32_16x16x32_bf16 v[12:15], v[178:181], v[210:213], v[12:15]
	v_mfma_f32_16x16x32_bf16 v[8:11], v[186:189], v[210:213], v[8:11]
	v_mfma_f32_16x16x32_bf16 v[4:7], v[178:181], v[218:221], v[4:7]
	v_mfma_f32_16x16x32_bf16 v[0:3], v[186:189], v[218:221], v[0:3]
	s_barrier
	s_setprio 0
	s_add_i32 s75, s75, 2
	s_add_u32 s34, s34, 0x100
	s_addc_u32 s35, s35, 0
	s_add_u32 s73, s73, 0x100
	s_addc_u32 s74, s74, 0
	s_cmp_gt_u32 s75, 29
	s_cbranch_scc0 .LBB0_744
	s_and_b64 vcc, exec, s[18:19]
	s_cbranch_vccz .LBB0_747
	s_barrier
